# EpiResid epilogues: residual loads also paired into 16-byte loads (registers permuted per row group, row offset recomputed), loads 32 to 16 per lane
# speedup vs baseline: 1.0209x; 1.0168x over previous
; #define PG8_GAS __attribute__((address_space(1)))
; __device__ __forceinline__ unsigned pk2_(float lo, float hi) { f32x2c_t v = {lo, hi}; bf16x2c_t b = __builtin_convertvector(v, bf16x2c_t); return __builtin_bit_cast(unsigned, b); }
;     __device__ __forceinline__ void operator()(const f32x4 (&acc)[2][2][4][2], const Unit& u, int wr, int wc, int fr, int fq) const {
;     ...
;         const int row0 = u.pm * BM + wr * 64 + fr, col0 = u.pn * BM + wc * 32 + 4 * fq;
;         u32x2v bsv[2][4][2][2];
; #pragma unroll
;         for (int ai = 0; ai < 2; ++ai)
; #pragma unroll
;             for (int m = 0; m < 4; ++m) { const size_t off = (size_t)(row0 + ai * HALF + m * 16) * 1024 + col0;
; #pragma unroll
;                 for (int bj = 0; bj < 2; ++bj)
; #pragma unroll
;                     for (int n = 0; n < 2; ++n) bsv[ai][m][bj][n] = *(const PG8_GAS u32x2v*)(hbase + off + bj * HALF + n * 16); }
; #pragma unroll
;         for (int ai = 0; ai < 2; ++ai)
; #pragma unroll
;             for (int m = 0; m < 4; ++m) {
;                 const int r = row0 + ai * HALF + m * 16; const size_t off = (size_t)r * 1024 + col0; float ss = 0.f;
; #pragma unroll
;                 for (int bj = 0; bj < 2; ++bj)
; #pragma unroll
;                     for (int n = 0; n < 2; ++n) {
;                         const u32x2v w0 = bsv[ai][m][bj][n]; f32x4 bs;
;                         bs[0] = __builtin_bit_cast(float, w0.x << 16); bs[1] = __builtin_bit_cast(float, w0.x & 0xffff0000u); bs[2] = __builtin_bit_cast(float, w0.y << 16); bs[3] = __builtin_bit_cast(float, w0.y & 0xffff0000u);
;                         const f32x4 v = bs + acc[ai][bj][m][n] * alpha;
;                         { u32x2v w; w.x = pk2_(v[0], v[1]); w.y = pk2_(v[2], v[3]); *(PG8_GAS u32x2v*)(hb + off + bj * HALF + n * 16) = w; }
;                         ss += (v[0] * v[0] + v[1] * v[1]) + (v[2] * v[2] + v[3] * v[3]);
;                     }
;                 ss += __shfl_xor(ss, 16); ss += __shfl_xor(ss, 32);
;                 if (fq == 0) ((PG8_GAS float*)parts)[(size_t)r * 16 + u.pn * 4 + wc] = ss;
;             }
.LBB0_771:
	s_lshl_b32 s34, s58, 8
	v_mov_b32_e32 v136, v252
	s_add_i32 s34, s34, s49
	v_and_b32_e32 v233, 64, v231
	v_and_or_b32 v220, v136, 15, s34
	s_lshl_b32 s34, s12, 8
	v_bfe_u32 v224, v136, 4, 2
	s_or_b32 s34, s34, s50
	v_lshl_or_b32 v138, v224, 2, s34
	v_ashrrev_i32_e32 v139, 31, v138
	v_lshlrev_b64 v[234:235], 1, v[138:139]
	v_ashrrev_i32_e32 v221, 31, v220
	v_lshl_add_u64 v[140:141], s[14:15], 0, v[234:235]
	v_lshlrev_b64 v[236:237], 11, v[220:221]
	v_lshl_add_u64 v[136:137], v[140:141], 0, v[236:237]
	v_bfe_u32 v250, v252, 4, 1
	v_mul_u32_u24_e32 v250, 24, v250
	v_mov_b32_e32 v251, 0
	v_lshl_add_u64 v[136:137], v[136:137], 0, v[250:251]
	global_load_dwordx4 v[238:241], v[136:137], off
	global_load_dwordx4 v[242:245], v[136:137], off offset:256
	v_or_b32_e32 v208, 16, v220
	v_ashrrev_i32_e32 v209, 31, v208
	v_or_b32_e32 v196, 32, v220
	v_lshlrev_b64 v[218:219], 11, v[208:209]
	v_ashrrev_i32_e32 v197, 31, v196
	v_or_b32_e32 v184, 48, v220
	v_lshl_add_u64 v[136:137], v[140:141], 0, v[218:219]
	v_lshlrev_b64 v[206:207], 11, v[196:197]
	v_ashrrev_i32_e32 v185, 31, v184
	v_add_u32_e32 v172, 0x80, v220
	v_lshl_add_u64 v[136:137], v[136:137], 0, v[250:251]
	global_load_dwordx4 v[216:219], v[136:137], off
	global_load_dwordx4 v[212:215], v[136:137], off offset:256
	v_lshl_add_u64 v[136:137], v[140:141], 0, v[206:207]
	v_lshlrev_b64 v[194:195], 11, v[184:185]
	v_ashrrev_i32_e32 v173, 31, v172
	v_add_u32_e32 v160, 0x90, v220
	v_lshl_add_u64 v[136:137], v[136:137], 0, v[250:251]
	global_load_dwordx4 v[204:207], v[136:137], off
	global_load_dwordx4 v[200:203], v[136:137], off offset:256
	v_lshl_add_u64 v[136:137], v[140:141], 0, v[194:195]
	v_lshlrev_b64 v[182:183], 11, v[172:173]
	v_ashrrev_i32_e32 v161, 31, v160
	v_add_u32_e32 v148, 0xa0, v220
	v_lshl_add_u64 v[136:137], v[136:137], 0, v[250:251]
	global_load_dwordx4 v[192:195], v[136:137], off
	global_load_dwordx4 v[188:191], v[136:137], off offset:256
	v_lshl_add_u64 v[136:137], v[140:141], 0, v[182:183]
	v_lshlrev_b64 v[170:171], 11, v[160:161]
	v_ashrrev_i32_e32 v149, 31, v148
	v_lshl_add_u64 v[136:137], v[136:137], 0, v[250:251]
	global_load_dwordx4 v[180:183], v[136:137], off
	global_load_dwordx4 v[176:179], v[136:137], off offset:256
	v_lshl_add_u64 v[136:137], v[140:141], 0, v[170:171]
	v_lshlrev_b64 v[158:159], 11, v[148:149]
	v_lshl_add_u64 v[136:137], v[136:137], 0, v[250:251]
	global_load_dwordx4 v[168:171], v[136:137], off
	global_load_dwordx4 v[164:167], v[136:137], off offset:256
	v_lshl_add_u64 v[136:137], v[140:141], 0, v[158:159]
	v_lshl_add_u64 v[136:137], v[136:137], 0, v[250:251]
	global_load_dwordx4 v[156:159], v[136:137], off
	global_load_dwordx4 v[152:155], v[136:137], off offset:256
	v_add_u32_e32 v136, 0xb0, v220
	v_ashrrev_i32_e32 v137, 31, v136
	v_lshlrev_b64 v[146:147], 11, v[136:137]
	v_lshl_add_u64 v[140:141], v[140:141], 0, v[146:147]
	v_lshl_add_u64 v[140:141], v[140:141], 0, v[250:251]
	global_load_dwordx4 v[144:147], v[140:141], off
	global_load_dwordx4 v[140:143], v[140:141], off offset:256
	s_nop 0
	v_xor_b32_e32 v232, 16, v231
	v_add_u32_e32 v233, 64, v233
	v_xor_b32_e32 v246, 32, v231
	v_cmp_lt_i32_e32 vcc, v232, v233
	v_lshl_add_u64 v[236:237], s[16:17], 0, v[236:237]
	s_lshl_b32 s34, s12, 2
	v_cndmask_b32_e32 v232, v231, v232, vcc
	v_cmp_lt_i32_e32 vcc, v246, v233
	v_lshlrev_b32_e32 v233, 2, v232
	v_lshl_add_u64 v[234:235], v[236:237], 0, v[234:235]
	v_cndmask_b32_e32 v246, v231, v246, vcc
	v_lshlrev_b32_e32 v232, 2, v246
	v_cmp_eq_u32_e32 vcc, 0, v224
	s_ashr_i32 s35, s34, 31
	s_waitcnt vmcnt(14)
	v_permlane16_swap_b32_e32 v238, v240
	v_permlane16_swap_b32_e32 v239, v241
	v_permlane16_swap_b32_e32 v242, v244
	v_permlane16_swap_b32_e32 v243, v245
	v_lshlrev_b32_e32 v246, 16, v238
	v_and_b32_e32 v247, 0xffff0000, v238
	v_lshlrev_b32_e32 v238, 16, v239
	v_and_b32_e32 v239, 0xffff0000, v239
	v_pk_fma_f32 v[124:125], v[124:125], 0.5, v[246:247] op_sel_hi:[1,0,1]
	v_pk_fma_f32 v[126:127], v[126:127], 0.5, v[238:239] op_sel_hi:[1,0,1]
	v_cvt_pk_bf16_f32 v238, v124, v125
	v_mul_f32_e32 v125, v125, v125
	v_fmac_f32_e32 v125, v124, v124
	v_mul_f32_e32 v124, v127, v127
	v_fmac_f32_e32 v124, v126, v126
	v_add_f32_e32 v224, v125, v124
	v_lshlrev_b32_e32 v124, 16, v240
	v_and_b32_e32 v125, 0xffff0000, v240
	v_cvt_pk_bf16_f32 v239, v126, v127
	v_lshlrev_b32_e32 v126, 16, v241
	v_and_b32_e32 v127, 0xffff0000, v241
	v_pk_fma_f32 v[120:121], v[120:121], 0.5, v[124:125] op_sel_hi:[1,0,1]
	v_pk_fma_f32 v[122:123], v[122:123], 0.5, v[126:127] op_sel_hi:[1,0,1]
	v_cvt_pk_bf16_f32 v124, v120, v121
	v_mul_f32_e32 v121, v121, v121
	v_fmac_f32_e32 v121, v120, v120
	v_mul_f32_e32 v120, v123, v123
	v_fmac_f32_e32 v120, v122, v122
	v_add_f32_e32 v120, v121, v120
	v_add_f32_e32 v125, v224, v120
	v_lshlrev_b32_e32 v120, 16, v242
	v_and_b32_e32 v121, 0xffff0000, v242
	v_lshlrev_b32_e32 v126, 16, v243
	v_and_b32_e32 v127, 0xffff0000, v243
	v_pk_fma_f32 v[118:119], v[118:119], 0.5, v[126:127] op_sel_hi:[1,0,1]
	v_pk_fma_f32 v[116:117], v[116:117], 0.5, v[120:121] op_sel_hi:[1,0,1]
	v_mul_f32_e32 v121, v119, v119
	v_mul_f32_e32 v120, v117, v117
	v_fmac_f32_e32 v120, v116, v116
	v_fmac_f32_e32 v121, v118, v118
	v_add_f32_e32 v120, v120, v121
	v_add_f32_e32 v125, v125, v120
	v_lshlrev_b32_e32 v120, 16, v244
	v_and_b32_e32 v121, 0xffff0000, v244
	v_lshlrev_b32_e32 v126, 16, v245
	v_and_b32_e32 v127, 0xffff0000, v245
	v_pk_fma_f32 v[114:115], v[114:115], 0.5, v[126:127] op_sel_hi:[1,0,1]
	v_pk_fma_f32 v[120:121], v[112:113], 0.5, v[120:121] op_sel_hi:[1,0,1]
	v_mul_f32_e32 v113, v115, v115
	v_mul_f32_e32 v112, v121, v121
	v_fmac_f32_e32 v112, v120, v120
	v_fmac_f32_e32 v113, v114, v114
	v_add_f32_e32 v112, v112, v113
	v_add_f32_e32 v112, v125, v112
	v_mov_b32_e32 v113, v112
	s_nop 1
	v_permlane16_swap_b32_e32 v112, v113
	v_cvt_pk_bf16_f32 v116, v116, v117
	v_cvt_pk_bf16_f32 v117, v118, v119
	v_cvt_pk_bf16_f32 v125, v122, v123
	global_store_dwordx2 v[234:235], v[116:117], off offset:256
	s_waitcnt lgkmcnt(0)
	v_add_f32_e32 v112, v112, v113
	v_mov_b32_e32 v113, v112
	s_nop 1
	v_permlane32_swap_b32_e32 v112, v113
	v_cvt_pk_bf16_f32 v116, v120, v121
	v_cvt_pk_bf16_f32 v117, v114, v115
	global_store_dwordx2 v[234:235], v[238:239], off
	global_store_dwordx2 v[234:235], v[124:125], off offset:32
	global_store_dwordx2 v[234:235], v[116:117], off offset:288
	s_and_saveexec_b64 s[36:37], vcc
	s_cbranch_execz .LBB0_773
	v_lshlrev_b64 v[114:115], 6, v[220:221]
	v_lshl_add_u64 v[114:115], s[18:19], 0, v[114:115]
	v_lshl_add_u64 v[114:115], s[34:35], 2, v[114:115]
	s_lshl_b32 s12, s48, 2
	v_lshl_add_u64 v[114:115], v[114:115], 0, s[12:13]
	s_waitcnt lgkmcnt(0)
	v_add_f32_e32 v112, v112, v113
	global_store_dword v[114:115], v112, off
; #define PG8_GAS __attribute__((address_space(1)))
; __device__ __forceinline__ unsigned pk2_(float lo, float hi) { f32x2c_t v = {lo, hi}; bf16x2c_t b = __builtin_convertvector(v, bf16x2c_t); return __builtin_bit_cast(unsigned, b); }
;     __device__ __forceinline__ void operator()(const f32x4 (&acc)[2][2][4][2], const Unit& u, int wr, int wc, int fr, int fq) const {
;     ...
;         for (int ai = 0; ai < 2; ++ai)
; #pragma unroll
;             for (int m = 0; m < 4; ++m) {
;                 const int r = row0 + ai * HALF + m * 16; const size_t off = (size_t)r * 1024 + col0; float ss = 0.f;
; #pragma unroll
;                 for (int bj = 0; bj < 2; ++bj)
; #pragma unroll
;                     for (int n = 0; n < 2; ++n) {
;                         const u32x2v w0 = bsv[ai][m][bj][n]; f32x4 bs;
;                         bs[0] = __builtin_bit_cast(float, w0.x << 16); bs[1] = __builtin_bit_cast(float, w0.x & 0xffff0000u); bs[2] = __builtin_bit_cast(float, w0.y << 16); bs[3] = __builtin_bit_cast(float, w0.y & 0xffff0000u);
;                         const f32x4 v = bs + acc[ai][bj][m][n] * alpha;
;                         { u32x2v w; w.x = pk2_(v[0], v[1]); w.y = pk2_(v[2], v[3]); *(PG8_GAS u32x2v*)(hb + off + bj * HALF + n * 16) = w; }
;                         ss += (v[0] * v[0] + v[1] * v[1]) + (v[2] * v[2] + v[3] * v[3]);
;                     }
;                 ss += __shfl_xor(ss, 16); ss += __shfl_xor(ss, 32);
;                 if (fq == 0) ((PG8_GAS float*)parts)[(size_t)r * 16 + u.pn * 4 + wc] = ss;
;             }
.LBB0_773:
	s_or_b64 exec, exec, s[36:37]
	s_waitcnt vmcnt(16)
	v_permlane16_swap_b32_e32 v216, v218
	v_permlane16_swap_b32_e32 v217, v219
	v_permlane16_swap_b32_e32 v212, v214
	v_permlane16_swap_b32_e32 v213, v215
	v_lshlrev_b64 v[222:223], 11, v[208:209]
	v_lshlrev_b32_e32 v112, 16, v216
	s_waitcnt lgkmcnt(0)
	v_and_b32_e32 v113, 0xffff0000, v216
	v_lshlrev_b32_e32 v114, 16, v217
	v_and_b32_e32 v115, 0xffff0000, v217
	v_pk_fma_f32 v[108:109], v[108:109], 0.5, v[112:113] op_sel_hi:[1,0,1]
	v_pk_fma_f32 v[110:111], v[110:111], 0.5, v[114:115] op_sel_hi:[1,0,1]
	v_cvt_pk_bf16_f32 v116, v108, v109
	v_mul_f32_e32 v109, v109, v109
	v_lshl_add_u64 v[114:115], s[16:17], 0, v[222:223]
	v_fmac_f32_e32 v109, v108, v108
	v_mul_f32_e32 v108, v111, v111
	v_cvt_pk_bf16_f32 v117, v110, v111
	v_lshl_add_u64 v[114:115], v[138:139], 1, v[114:115]
	v_fmac_f32_e32 v108, v110, v110
	v_add_f32_e32 v112, v109, v108
	v_lshlrev_b32_e32 v108, 16, v218
	v_and_b32_e32 v109, 0xffff0000, v218
	v_lshlrev_b32_e32 v110, 16, v219
	v_and_b32_e32 v111, 0xffff0000, v219
	v_pk_fma_f32 v[104:105], v[104:105], 0.5, v[108:109] op_sel_hi:[1,0,1]
	v_pk_fma_f32 v[106:107], v[106:107], 0.5, v[110:111] op_sel_hi:[1,0,1]
	v_cvt_pk_bf16_f32 v118, v104, v105
	v_mul_f32_e32 v105, v105, v105
	v_fmac_f32_e32 v105, v104, v104
	v_mul_f32_e32 v104, v107, v107
	v_fmac_f32_e32 v104, v106, v106
	v_add_f32_e32 v104, v105, v104
	v_add_f32_e32 v109, v112, v104
	v_lshlrev_b32_e32 v104, 16, v212
	v_and_b32_e32 v105, 0xffff0000, v212
	v_lshlrev_b32_e32 v110, 16, v213
	v_and_b32_e32 v111, 0xffff0000, v213
	v_pk_fma_f32 v[102:103], v[102:103], 0.5, v[110:111] op_sel_hi:[1,0,1]
	v_pk_fma_f32 v[100:101], v[100:101], 0.5, v[104:105] op_sel_hi:[1,0,1]
	v_mul_f32_e32 v105, v103, v103
	v_mul_f32_e32 v104, v101, v101
	v_fmac_f32_e32 v104, v100, v100
	v_fmac_f32_e32 v105, v102, v102
	v_add_f32_e32 v104, v104, v105
	v_add_f32_e32 v109, v109, v104
	v_lshlrev_b32_e32 v104, 16, v214
	v_and_b32_e32 v105, 0xffff0000, v214
	v_lshlrev_b32_e32 v110, 16, v215
	v_and_b32_e32 v111, 0xffff0000, v215
	v_pk_fma_f32 v[98:99], v[98:99], 0.5, v[110:111] op_sel_hi:[1,0,1]
	v_pk_fma_f32 v[104:105], v[96:97], 0.5, v[104:105] op_sel_hi:[1,0,1]
	v_mul_f32_e32 v97, v99, v99
	v_mul_f32_e32 v96, v105, v105
	v_fmac_f32_e32 v96, v104, v104
	v_fmac_f32_e32 v97, v98, v98
	v_add_f32_e32 v96, v96, v97
	v_add_f32_e32 v96, v109, v96
	v_mov_b32_e32 v97, v96
	s_nop 1
	v_permlane16_swap_b32_e32 v96, v97
	v_cvt_pk_bf16_f32 v110, v100, v101
	v_cvt_pk_bf16_f32 v111, v102, v103
	v_cvt_pk_bf16_f32 v119, v106, v107
	s_waitcnt lgkmcnt(0)
	v_add_f32_e32 v96, v96, v97
	v_mov_b32_e32 v97, v96
	s_nop 1
	v_permlane32_swap_b32_e32 v96, v97
	v_cvt_pk_bf16_f32 v112, v104, v105
	v_cvt_pk_bf16_f32 v113, v98, v99
	v_lshl_add_u64 v[114:115], v[114:115], 0, v[250:251]
	s_nop 1
	v_permlane16_swap_b32_e32 v116, v118
	v_permlane16_swap_b32_e32 v117, v119
	global_store_dwordx4 v[114:115], v[116:119], off
	s_nop 1
	s_nop 1
	v_permlane16_swap_b32_e32 v110, v112
	v_permlane16_swap_b32_e32 v111, v113
	global_store_dwordx4 v[114:115], v[110:113], off offset:256
	s_nop 1
	s_and_saveexec_b64 s[36:37], vcc
	s_cbranch_execz .LBB0_775
	v_lshlrev_b64 v[98:99], 6, v[208:209]
	v_lshl_add_u64 v[98:99], s[18:19], 0, v[98:99]
	v_lshl_add_u64 v[98:99], s[34:35], 2, v[98:99]
	s_lshl_b32 s12, s48, 2
	v_lshl_add_u64 v[98:99], v[98:99], 0, s[12:13]
	s_waitcnt lgkmcnt(0)
	v_add_f32_e32 v96, v96, v97
	global_store_dword v[98:99], v96, off
.LBB0_775:
	s_or_b64 exec, exec, s[36:37]
	s_waitcnt vmcnt(16)
	v_permlane16_swap_b32_e32 v204, v206
	v_permlane16_swap_b32_e32 v205, v207
	v_permlane16_swap_b32_e32 v200, v202
	v_permlane16_swap_b32_e32 v201, v203
	v_lshlrev_b64 v[210:211], 11, v[196:197]
	v_lshlrev_b32_e32 v96, 16, v204
	s_waitcnt lgkmcnt(0)
	v_and_b32_e32 v97, 0xffff0000, v204
	v_lshlrev_b32_e32 v98, 16, v205
	v_and_b32_e32 v99, 0xffff0000, v205
	v_pk_fma_f32 v[92:93], v[92:93], 0.5, v[96:97] op_sel_hi:[1,0,1]
	v_pk_fma_f32 v[94:95], v[94:95], 0.5, v[98:99] op_sel_hi:[1,0,1]
	v_cvt_pk_bf16_f32 v100, v92, v93
	v_mul_f32_e32 v93, v93, v93
	v_lshl_add_u64 v[98:99], s[16:17], 0, v[210:211]
	v_fmac_f32_e32 v93, v92, v92
	v_mul_f32_e32 v92, v95, v95
	v_cvt_pk_bf16_f32 v101, v94, v95
	v_lshl_add_u64 v[98:99], v[138:139], 1, v[98:99]
	v_fmac_f32_e32 v92, v94, v94
	v_add_f32_e32 v96, v93, v92
	v_lshlrev_b32_e32 v92, 16, v206
	v_and_b32_e32 v93, 0xffff0000, v206
	v_lshlrev_b32_e32 v94, 16, v207
	v_and_b32_e32 v95, 0xffff0000, v207
	v_pk_fma_f32 v[88:89], v[88:89], 0.5, v[92:93] op_sel_hi:[1,0,1]
	v_pk_fma_f32 v[90:91], v[90:91], 0.5, v[94:95] op_sel_hi:[1,0,1]
	v_cvt_pk_bf16_f32 v102, v88, v89
	v_mul_f32_e32 v89, v89, v89
	v_fmac_f32_e32 v89, v88, v88
	v_mul_f32_e32 v88, v91, v91
	v_fmac_f32_e32 v88, v90, v90
	v_add_f32_e32 v88, v89, v88
	v_add_f32_e32 v93, v96, v88
	v_lshlrev_b32_e32 v88, 16, v200
	v_and_b32_e32 v89, 0xffff0000, v200
	v_lshlrev_b32_e32 v94, 16, v201
	v_and_b32_e32 v95, 0xffff0000, v201
	v_pk_fma_f32 v[86:87], v[86:87], 0.5, v[94:95] op_sel_hi:[1,0,1]
	v_pk_fma_f32 v[84:85], v[84:85], 0.5, v[88:89] op_sel_hi:[1,0,1]
	v_mul_f32_e32 v89, v87, v87
	v_mul_f32_e32 v88, v85, v85
	v_fmac_f32_e32 v88, v84, v84
	v_fmac_f32_e32 v89, v86, v86
	v_add_f32_e32 v88, v88, v89
	v_add_f32_e32 v93, v93, v88
	v_lshlrev_b32_e32 v88, 16, v202
	v_and_b32_e32 v89, 0xffff0000, v202
	v_lshlrev_b32_e32 v94, 16, v203
	v_and_b32_e32 v95, 0xffff0000, v203
	v_pk_fma_f32 v[82:83], v[82:83], 0.5, v[94:95] op_sel_hi:[1,0,1]
	v_pk_fma_f32 v[88:89], v[80:81], 0.5, v[88:89] op_sel_hi:[1,0,1]
	v_mul_f32_e32 v81, v83, v83
	v_mul_f32_e32 v80, v89, v89
	v_fmac_f32_e32 v80, v88, v88
	v_fmac_f32_e32 v81, v82, v82
	v_add_f32_e32 v80, v80, v81
	v_add_f32_e32 v80, v93, v80
	v_mov_b32_e32 v81, v80
	s_nop 1
	v_permlane16_swap_b32_e32 v80, v81
	v_cvt_pk_bf16_f32 v94, v84, v85
	v_cvt_pk_bf16_f32 v95, v86, v87
	v_cvt_pk_bf16_f32 v103, v90, v91
	s_waitcnt lgkmcnt(0)
	v_add_f32_e32 v80, v80, v81
	v_mov_b32_e32 v81, v80
	s_nop 1
	v_permlane32_swap_b32_e32 v80, v81
	v_cvt_pk_bf16_f32 v96, v88, v89
	v_cvt_pk_bf16_f32 v97, v82, v83
	v_lshl_add_u64 v[98:99], v[98:99], 0, v[250:251]
	s_nop 1
	v_permlane16_swap_b32_e32 v100, v102
	v_permlane16_swap_b32_e32 v101, v103
	global_store_dwordx4 v[98:99], v[100:103], off
	s_nop 1
	s_nop 1
	v_permlane16_swap_b32_e32 v94, v96
	v_permlane16_swap_b32_e32 v95, v97
	global_store_dwordx4 v[98:99], v[94:97], off offset:256
	s_nop 1
	s_and_saveexec_b64 s[36:37], vcc
	s_cbranch_execz .LBB0_777
	v_lshlrev_b64 v[82:83], 6, v[196:197]
	v_lshl_add_u64 v[82:83], s[18:19], 0, v[82:83]
	v_lshl_add_u64 v[82:83], s[34:35], 2, v[82:83]
	s_lshl_b32 s12, s48, 2
	v_lshl_add_u64 v[82:83], v[82:83], 0, s[12:13]
	s_waitcnt lgkmcnt(0)
	v_add_f32_e32 v80, v80, v81
	global_store_dword v[82:83], v80, off
; #define PG8_GAS __attribute__((address_space(1)))
; __device__ __forceinline__ unsigned pk2_(float lo, float hi) { f32x2c_t v = {lo, hi}; bf16x2c_t b = __builtin_convertvector(v, bf16x2c_t); return __builtin_bit_cast(unsigned, b); }
;     __device__ __forceinline__ void operator()(const f32x4 (&acc)[2][2][4][2], const Unit& u, int wr, int wc, int fr, int fq) const {
;     ...
;         for (int ai = 0; ai < 2; ++ai)
; #pragma unroll
;             for (int m = 0; m < 4; ++m) {
;                 const int r = row0 + ai * HALF + m * 16; const size_t off = (size_t)r * 1024 + col0; float ss = 0.f;
; #pragma unroll
;                 for (int bj = 0; bj < 2; ++bj)
; #pragma unroll
;                     for (int n = 0; n < 2; ++n) {
;                         const u32x2v w0 = bsv[ai][m][bj][n]; f32x4 bs;
;                         bs[0] = __builtin_bit_cast(float, w0.x << 16); bs[1] = __builtin_bit_cast(float, w0.x & 0xffff0000u); bs[2] = __builtin_bit_cast(float, w0.y << 16); bs[3] = __builtin_bit_cast(float, w0.y & 0xffff0000u);
;                         const f32x4 v = bs + acc[ai][bj][m][n] * alpha;
;                         { u32x2v w; w.x = pk2_(v[0], v[1]); w.y = pk2_(v[2], v[3]); *(PG8_GAS u32x2v*)(hb + off + bj * HALF + n * 16) = w; }
;                         ss += (v[0] * v[0] + v[1] * v[1]) + (v[2] * v[2] + v[3] * v[3]);
;                     }
;                 ss += __shfl_xor(ss, 16); ss += __shfl_xor(ss, 32);
;                 if (fq == 0) ((PG8_GAS float*)parts)[(size_t)r * 16 + u.pn * 4 + wc] = ss;
;             }
.LBB0_777:
	s_or_b64 exec, exec, s[36:37]
	s_waitcnt vmcnt(16)
	v_permlane16_swap_b32_e32 v192, v194
	v_permlane16_swap_b32_e32 v193, v195
	v_permlane16_swap_b32_e32 v188, v190
	v_permlane16_swap_b32_e32 v189, v191
	v_lshlrev_b64 v[198:199], 11, v[184:185]
	v_lshlrev_b32_e32 v80, 16, v192
	s_waitcnt lgkmcnt(0)
	v_and_b32_e32 v81, 0xffff0000, v192
	v_lshlrev_b32_e32 v82, 16, v193
	v_and_b32_e32 v83, 0xffff0000, v193
	v_pk_fma_f32 v[76:77], v[76:77], 0.5, v[80:81] op_sel_hi:[1,0,1]
	v_pk_fma_f32 v[78:79], v[78:79], 0.5, v[82:83] op_sel_hi:[1,0,1]
	v_cvt_pk_bf16_f32 v84, v76, v77
	v_mul_f32_e32 v77, v77, v77
	v_lshl_add_u64 v[82:83], s[16:17], 0, v[198:199]
	v_fmac_f32_e32 v77, v76, v76
	v_mul_f32_e32 v76, v79, v79
	v_cvt_pk_bf16_f32 v85, v78, v79
	v_lshl_add_u64 v[82:83], v[138:139], 1, v[82:83]
	v_fmac_f32_e32 v76, v78, v78
	v_add_f32_e32 v80, v77, v76
	v_lshlrev_b32_e32 v76, 16, v194
	v_and_b32_e32 v77, 0xffff0000, v194
	v_lshlrev_b32_e32 v78, 16, v195
	v_and_b32_e32 v79, 0xffff0000, v195
	v_pk_fma_f32 v[72:73], v[72:73], 0.5, v[76:77] op_sel_hi:[1,0,1]
	v_pk_fma_f32 v[74:75], v[74:75], 0.5, v[78:79] op_sel_hi:[1,0,1]
	v_cvt_pk_bf16_f32 v86, v72, v73
	v_mul_f32_e32 v73, v73, v73
	v_fmac_f32_e32 v73, v72, v72
	v_mul_f32_e32 v72, v75, v75
	v_fmac_f32_e32 v72, v74, v74
	v_add_f32_e32 v72, v73, v72
	v_add_f32_e32 v77, v80, v72
	v_lshlrev_b32_e32 v72, 16, v188
	v_and_b32_e32 v73, 0xffff0000, v188
	v_lshlrev_b32_e32 v78, 16, v189
	v_and_b32_e32 v79, 0xffff0000, v189
	v_pk_fma_f32 v[70:71], v[70:71], 0.5, v[78:79] op_sel_hi:[1,0,1]
	v_pk_fma_f32 v[68:69], v[68:69], 0.5, v[72:73] op_sel_hi:[1,0,1]
	v_mul_f32_e32 v73, v71, v71
	v_mul_f32_e32 v72, v69, v69
	v_fmac_f32_e32 v72, v68, v68
	v_fmac_f32_e32 v73, v70, v70
	v_add_f32_e32 v72, v72, v73
	v_add_f32_e32 v77, v77, v72
	v_lshlrev_b32_e32 v72, 16, v190
	v_and_b32_e32 v73, 0xffff0000, v190
	v_lshlrev_b32_e32 v78, 16, v191
	v_and_b32_e32 v79, 0xffff0000, v191
	v_pk_fma_f32 v[66:67], v[66:67], 0.5, v[78:79] op_sel_hi:[1,0,1]
	v_pk_fma_f32 v[72:73], v[64:65], 0.5, v[72:73] op_sel_hi:[1,0,1]
	v_mul_f32_e32 v65, v67, v67
	v_mul_f32_e32 v64, v73, v73
	v_fmac_f32_e32 v64, v72, v72
	v_fmac_f32_e32 v65, v66, v66
	v_add_f32_e32 v64, v64, v65
	v_add_f32_e32 v64, v77, v64
	v_mov_b32_e32 v65, v64
	s_nop 1
	v_permlane16_swap_b32_e32 v64, v65
	v_cvt_pk_bf16_f32 v78, v68, v69
	v_cvt_pk_bf16_f32 v79, v70, v71
	v_cvt_pk_bf16_f32 v87, v74, v75
	s_waitcnt lgkmcnt(0)
	v_add_f32_e32 v64, v64, v65
	v_mov_b32_e32 v65, v64
	s_nop 1
	v_permlane32_swap_b32_e32 v64, v65
	v_cvt_pk_bf16_f32 v80, v72, v73
	v_cvt_pk_bf16_f32 v81, v66, v67
	v_lshl_add_u64 v[82:83], v[82:83], 0, v[250:251]
	s_nop 1
	v_permlane16_swap_b32_e32 v84, v86
	v_permlane16_swap_b32_e32 v85, v87
	global_store_dwordx4 v[82:83], v[84:87], off
	s_nop 1
	s_nop 1
	v_permlane16_swap_b32_e32 v78, v80
	v_permlane16_swap_b32_e32 v79, v81
	global_store_dwordx4 v[82:83], v[78:81], off offset:256
	s_nop 1
	s_and_saveexec_b64 s[36:37], vcc
	s_cbranch_execz .LBB0_779
	v_lshlrev_b64 v[66:67], 6, v[184:185]
	v_lshl_add_u64 v[66:67], s[18:19], 0, v[66:67]
	v_lshl_add_u64 v[66:67], s[34:35], 2, v[66:67]
	s_lshl_b32 s12, s48, 2
	v_lshl_add_u64 v[66:67], v[66:67], 0, s[12:13]
	s_waitcnt lgkmcnt(0)
	v_add_f32_e32 v64, v64, v65
	global_store_dword v[66:67], v64, off
.LBB0_779:
	s_or_b64 exec, exec, s[36:37]
	s_waitcnt vmcnt(16)
	v_permlane16_swap_b32_e32 v180, v182
	v_permlane16_swap_b32_e32 v181, v183
	v_permlane16_swap_b32_e32 v176, v178
	v_permlane16_swap_b32_e32 v177, v179
	v_lshlrev_b64 v[186:187], 11, v[172:173]
	v_lshlrev_b32_e32 v64, 16, v180
	s_waitcnt lgkmcnt(0)
	v_and_b32_e32 v65, 0xffff0000, v180
	v_lshlrev_b32_e32 v66, 16, v181
	v_and_b32_e32 v67, 0xffff0000, v181
	v_pk_fma_f32 v[60:61], v[60:61], 0.5, v[64:65] op_sel_hi:[1,0,1]
	v_pk_fma_f32 v[62:63], v[62:63], 0.5, v[66:67] op_sel_hi:[1,0,1]
	v_cvt_pk_bf16_f32 v68, v60, v61
	v_mul_f32_e32 v61, v61, v61
	v_lshl_add_u64 v[66:67], s[16:17], 0, v[186:187]
	v_fmac_f32_e32 v61, v60, v60
	v_mul_f32_e32 v60, v63, v63
	v_cvt_pk_bf16_f32 v69, v62, v63
	v_lshl_add_u64 v[66:67], v[138:139], 1, v[66:67]
	v_fmac_f32_e32 v60, v62, v62
	v_add_f32_e32 v64, v61, v60
	v_lshlrev_b32_e32 v60, 16, v182
	v_and_b32_e32 v61, 0xffff0000, v182
	v_lshlrev_b32_e32 v62, 16, v183
	v_and_b32_e32 v63, 0xffff0000, v183
	v_pk_fma_f32 v[56:57], v[56:57], 0.5, v[60:61] op_sel_hi:[1,0,1]
	v_pk_fma_f32 v[58:59], v[58:59], 0.5, v[62:63] op_sel_hi:[1,0,1]
	v_cvt_pk_bf16_f32 v70, v56, v57
	v_mul_f32_e32 v57, v57, v57
	v_fmac_f32_e32 v57, v56, v56
	v_mul_f32_e32 v56, v59, v59
	v_fmac_f32_e32 v56, v58, v58
	v_add_f32_e32 v56, v57, v56
	v_add_f32_e32 v61, v64, v56
	v_lshlrev_b32_e32 v56, 16, v176
	v_and_b32_e32 v57, 0xffff0000, v176
	v_lshlrev_b32_e32 v62, 16, v177
	v_and_b32_e32 v63, 0xffff0000, v177
	v_pk_fma_f32 v[54:55], v[54:55], 0.5, v[62:63] op_sel_hi:[1,0,1]
	v_pk_fma_f32 v[52:53], v[52:53], 0.5, v[56:57] op_sel_hi:[1,0,1]
	v_mul_f32_e32 v57, v55, v55
	v_mul_f32_e32 v56, v53, v53
	v_fmac_f32_e32 v56, v52, v52
	v_fmac_f32_e32 v57, v54, v54
	v_add_f32_e32 v56, v56, v57
	v_add_f32_e32 v61, v61, v56
	v_lshlrev_b32_e32 v56, 16, v178
	v_and_b32_e32 v57, 0xffff0000, v178
	v_lshlrev_b32_e32 v62, 16, v179
	v_and_b32_e32 v63, 0xffff0000, v179
	v_pk_fma_f32 v[50:51], v[50:51], 0.5, v[62:63] op_sel_hi:[1,0,1]
	v_pk_fma_f32 v[56:57], v[48:49], 0.5, v[56:57] op_sel_hi:[1,0,1]
	v_mul_f32_e32 v49, v51, v51
	v_mul_f32_e32 v48, v57, v57
	v_fmac_f32_e32 v48, v56, v56
	v_fmac_f32_e32 v49, v50, v50
	v_add_f32_e32 v48, v48, v49
	v_add_f32_e32 v48, v61, v48
	v_mov_b32_e32 v49, v48
	s_nop 1
	v_permlane16_swap_b32_e32 v48, v49
	v_cvt_pk_bf16_f32 v62, v52, v53
	v_cvt_pk_bf16_f32 v63, v54, v55
	v_cvt_pk_bf16_f32 v71, v58, v59
	s_waitcnt lgkmcnt(0)
	v_add_f32_e32 v48, v48, v49
	v_mov_b32_e32 v49, v48
	s_nop 1
	v_permlane32_swap_b32_e32 v48, v49
	v_cvt_pk_bf16_f32 v64, v56, v57
	v_cvt_pk_bf16_f32 v65, v50, v51
	v_lshl_add_u64 v[66:67], v[66:67], 0, v[250:251]
	s_nop 1
	v_permlane16_swap_b32_e32 v68, v70
	v_permlane16_swap_b32_e32 v69, v71
	global_store_dwordx4 v[66:67], v[68:71], off
	s_nop 1
	s_nop 1
	v_permlane16_swap_b32_e32 v62, v64
	v_permlane16_swap_b32_e32 v63, v65
	global_store_dwordx4 v[66:67], v[62:65], off offset:256
	s_nop 1
	s_and_saveexec_b64 s[36:37], vcc
	s_cbranch_execz .LBB0_781
	v_lshlrev_b64 v[50:51], 6, v[172:173]
	v_lshl_add_u64 v[50:51], s[18:19], 0, v[50:51]
	v_lshl_add_u64 v[50:51], s[34:35], 2, v[50:51]
	s_lshl_b32 s12, s48, 2
	v_lshl_add_u64 v[50:51], v[50:51], 0, s[12:13]
	s_waitcnt lgkmcnt(0)
	v_add_f32_e32 v48, v48, v49
	global_store_dword v[50:51], v48, off
; #define PG8_GAS __attribute__((address_space(1)))
; __device__ __forceinline__ unsigned pk2_(float lo, float hi) { f32x2c_t v = {lo, hi}; bf16x2c_t b = __builtin_convertvector(v, bf16x2c_t); return __builtin_bit_cast(unsigned, b); }
;     __device__ __forceinline__ void operator()(const f32x4 (&acc)[2][2][4][2], const Unit& u, int wr, int wc, int fr, int fq) const {
;     ...
;         for (int ai = 0; ai < 2; ++ai)
; #pragma unroll
;             for (int m = 0; m < 4; ++m) {
;                 const int r = row0 + ai * HALF + m * 16; const size_t off = (size_t)r * 1024 + col0; float ss = 0.f;
; #pragma unroll
;                 for (int bj = 0; bj < 2; ++bj)
; #pragma unroll
;                     for (int n = 0; n < 2; ++n) {
;                         const u32x2v w0 = bsv[ai][m][bj][n]; f32x4 bs;
;                         bs[0] = __builtin_bit_cast(float, w0.x << 16); bs[1] = __builtin_bit_cast(float, w0.x & 0xffff0000u); bs[2] = __builtin_bit_cast(float, w0.y << 16); bs[3] = __builtin_bit_cast(float, w0.y & 0xffff0000u);
;                         const f32x4 v = bs + acc[ai][bj][m][n] * alpha;
;                         { u32x2v w; w.x = pk2_(v[0], v[1]); w.y = pk2_(v[2], v[3]); *(PG8_GAS u32x2v*)(hb + off + bj * HALF + n * 16) = w; }
;                         ss += (v[0] * v[0] + v[1] * v[1]) + (v[2] * v[2] + v[3] * v[3]);
;                     }
;                 ss += __shfl_xor(ss, 16); ss += __shfl_xor(ss, 32);
;                 if (fq == 0) ((PG8_GAS float*)parts)[(size_t)r * 16 + u.pn * 4 + wc] = ss;
;             }
.LBB0_781:
	s_or_b64 exec, exec, s[36:37]
	s_waitcnt vmcnt(16)
	v_permlane16_swap_b32_e32 v168, v170
	v_permlane16_swap_b32_e32 v169, v171
	v_permlane16_swap_b32_e32 v164, v166
	v_permlane16_swap_b32_e32 v165, v167
	v_lshlrev_b64 v[174:175], 11, v[160:161]
	v_lshlrev_b32_e32 v48, 16, v168
	s_waitcnt lgkmcnt(0)
	v_and_b32_e32 v49, 0xffff0000, v168
	v_lshlrev_b32_e32 v50, 16, v169
	v_and_b32_e32 v51, 0xffff0000, v169
	v_pk_fma_f32 v[44:45], v[44:45], 0.5, v[48:49] op_sel_hi:[1,0,1]
	v_pk_fma_f32 v[46:47], v[46:47], 0.5, v[50:51] op_sel_hi:[1,0,1]
	v_cvt_pk_bf16_f32 v52, v44, v45
	v_mul_f32_e32 v45, v45, v45
	v_lshl_add_u64 v[50:51], s[16:17], 0, v[174:175]
	v_fmac_f32_e32 v45, v44, v44
	v_mul_f32_e32 v44, v47, v47
	v_cvt_pk_bf16_f32 v53, v46, v47
	v_lshl_add_u64 v[50:51], v[138:139], 1, v[50:51]
	v_fmac_f32_e32 v44, v46, v46
	v_add_f32_e32 v48, v45, v44
	v_lshlrev_b32_e32 v44, 16, v170
	v_and_b32_e32 v45, 0xffff0000, v170
	v_lshlrev_b32_e32 v46, 16, v171
	v_and_b32_e32 v47, 0xffff0000, v171
	v_pk_fma_f32 v[40:41], v[40:41], 0.5, v[44:45] op_sel_hi:[1,0,1]
	v_pk_fma_f32 v[42:43], v[42:43], 0.5, v[46:47] op_sel_hi:[1,0,1]
	v_cvt_pk_bf16_f32 v54, v40, v41
	v_mul_f32_e32 v41, v41, v41
	v_fmac_f32_e32 v41, v40, v40
	v_mul_f32_e32 v40, v43, v43
	v_fmac_f32_e32 v40, v42, v42
	v_add_f32_e32 v40, v41, v40
	v_add_f32_e32 v45, v48, v40
	v_lshlrev_b32_e32 v40, 16, v164
	v_and_b32_e32 v41, 0xffff0000, v164
	v_lshlrev_b32_e32 v46, 16, v165
	v_and_b32_e32 v47, 0xffff0000, v165
	v_pk_fma_f32 v[38:39], v[38:39], 0.5, v[46:47] op_sel_hi:[1,0,1]
	v_pk_fma_f32 v[36:37], v[36:37], 0.5, v[40:41] op_sel_hi:[1,0,1]
	v_mul_f32_e32 v41, v39, v39
	v_mul_f32_e32 v40, v37, v37
	v_fmac_f32_e32 v40, v36, v36
	v_fmac_f32_e32 v41, v38, v38
	v_add_f32_e32 v40, v40, v41
	v_add_f32_e32 v45, v45, v40
	v_lshlrev_b32_e32 v40, 16, v166
	v_and_b32_e32 v41, 0xffff0000, v166
	v_lshlrev_b32_e32 v46, 16, v167
	v_and_b32_e32 v47, 0xffff0000, v167
	v_pk_fma_f32 v[34:35], v[34:35], 0.5, v[46:47] op_sel_hi:[1,0,1]
	v_pk_fma_f32 v[40:41], v[32:33], 0.5, v[40:41] op_sel_hi:[1,0,1]
	v_mul_f32_e32 v33, v35, v35
	v_mul_f32_e32 v32, v41, v41
	v_fmac_f32_e32 v32, v40, v40
	v_fmac_f32_e32 v33, v34, v34
	v_add_f32_e32 v32, v32, v33
	v_add_f32_e32 v32, v45, v32
	v_mov_b32_e32 v33, v32
	s_nop 1
	v_permlane16_swap_b32_e32 v32, v33
	v_cvt_pk_bf16_f32 v46, v36, v37
	v_cvt_pk_bf16_f32 v47, v38, v39
	v_cvt_pk_bf16_f32 v55, v42, v43
	s_waitcnt lgkmcnt(0)
	v_add_f32_e32 v32, v32, v33
	v_mov_b32_e32 v33, v32
	s_nop 1
	v_permlane32_swap_b32_e32 v32, v33
	v_cvt_pk_bf16_f32 v48, v40, v41
	v_cvt_pk_bf16_f32 v49, v34, v35
	v_lshl_add_u64 v[50:51], v[50:51], 0, v[250:251]
	s_nop 1
	v_permlane16_swap_b32_e32 v52, v54
	v_permlane16_swap_b32_e32 v53, v55
	global_store_dwordx4 v[50:51], v[52:55], off
	s_nop 1
	s_nop 1
	v_permlane16_swap_b32_e32 v46, v48
	v_permlane16_swap_b32_e32 v47, v49
	global_store_dwordx4 v[50:51], v[46:49], off offset:256
	s_nop 1
	s_and_saveexec_b64 s[36:37], vcc
	s_cbranch_execz .LBB0_783
	v_lshlrev_b64 v[34:35], 6, v[160:161]
	v_lshl_add_u64 v[34:35], s[18:19], 0, v[34:35]
	v_lshl_add_u64 v[34:35], s[34:35], 2, v[34:35]
	s_lshl_b32 s12, s48, 2
	v_lshl_add_u64 v[34:35], v[34:35], 0, s[12:13]
	s_waitcnt lgkmcnt(0)
	v_add_f32_e32 v32, v32, v33
	global_store_dword v[34:35], v32, off
; #define PG8_GAS __attribute__((address_space(1)))
; __device__ __forceinline__ unsigned pk2_(float lo, float hi) { f32x2c_t v = {lo, hi}; bf16x2c_t b = __builtin_convertvector(v, bf16x2c_t); return __builtin_bit_cast(unsigned, b); }
;     __device__ __forceinline__ void operator()(const f32x4 (&acc)[2][2][4][2], const Unit& u, int wr, int wc, int fr, int fq) const {
;     ...
;         for (int ai = 0; ai < 2; ++ai)
; #pragma unroll
;             for (int m = 0; m < 4; ++m) {
;                 const int r = row0 + ai * HALF + m * 16; const size_t off = (size_t)r * 1024 + col0; float ss = 0.f;
; #pragma unroll
;                 for (int bj = 0; bj < 2; ++bj)
; #pragma unroll
;                     for (int n = 0; n < 2; ++n) {
;                         const u32x2v w0 = bsv[ai][m][bj][n]; f32x4 bs;
;                         bs[0] = __builtin_bit_cast(float, w0.x << 16); bs[1] = __builtin_bit_cast(float, w0.x & 0xffff0000u); bs[2] = __builtin_bit_cast(float, w0.y << 16); bs[3] = __builtin_bit_cast(float, w0.y & 0xffff0000u);
;                         const f32x4 v = bs + acc[ai][bj][m][n] * alpha;
;                         { u32x2v w; w.x = pk2_(v[0], v[1]); w.y = pk2_(v[2], v[3]); *(PG8_GAS u32x2v*)(hb + off + bj * HALF + n * 16) = w; }
;                         ss += (v[0] * v[0] + v[1] * v[1]) + (v[2] * v[2] + v[3] * v[3]);
;                     }
;                 ss += __shfl_xor(ss, 16); ss += __shfl_xor(ss, 32);
;                 if (fq == 0) ((PG8_GAS float*)parts)[(size_t)r * 16 + u.pn * 4 + wc] = ss;
;             }
.LBB0_783:
	s_or_b64 exec, exec, s[36:37]
	s_waitcnt vmcnt(16)
	v_permlane16_swap_b32_e32 v156, v158
	v_permlane16_swap_b32_e32 v157, v159
	v_permlane16_swap_b32_e32 v152, v154
	v_permlane16_swap_b32_e32 v153, v155
	v_lshlrev_b64 v[162:163], 11, v[148:149]
	v_lshlrev_b32_e32 v32, 16, v156
	s_waitcnt lgkmcnt(0)
	v_and_b32_e32 v33, 0xffff0000, v156
	v_lshlrev_b32_e32 v34, 16, v157
	v_and_b32_e32 v35, 0xffff0000, v157
	v_pk_fma_f32 v[28:29], v[28:29], 0.5, v[32:33] op_sel_hi:[1,0,1]
	v_pk_fma_f32 v[30:31], v[30:31], 0.5, v[34:35] op_sel_hi:[1,0,1]
	v_cvt_pk_bf16_f32 v36, v28, v29
	v_mul_f32_e32 v29, v29, v29
	v_lshl_add_u64 v[34:35], s[16:17], 0, v[162:163]
	v_fmac_f32_e32 v29, v28, v28
	v_mul_f32_e32 v28, v31, v31
	v_cvt_pk_bf16_f32 v37, v30, v31
	v_lshl_add_u64 v[34:35], v[138:139], 1, v[34:35]
	v_fmac_f32_e32 v28, v30, v30
	v_add_f32_e32 v32, v29, v28
	v_lshlrev_b32_e32 v28, 16, v158
	v_and_b32_e32 v29, 0xffff0000, v158
	v_lshlrev_b32_e32 v30, 16, v159
	v_and_b32_e32 v31, 0xffff0000, v159
	v_pk_fma_f32 v[24:25], v[24:25], 0.5, v[28:29] op_sel_hi:[1,0,1]
	v_pk_fma_f32 v[26:27], v[26:27], 0.5, v[30:31] op_sel_hi:[1,0,1]
	v_cvt_pk_bf16_f32 v38, v24, v25
	v_mul_f32_e32 v25, v25, v25
	v_fmac_f32_e32 v25, v24, v24
	v_mul_f32_e32 v24, v27, v27
	v_fmac_f32_e32 v24, v26, v26
	v_add_f32_e32 v24, v25, v24
	v_add_f32_e32 v29, v32, v24
	v_lshlrev_b32_e32 v24, 16, v152
	v_and_b32_e32 v25, 0xffff0000, v152
	v_lshlrev_b32_e32 v30, 16, v153
	v_and_b32_e32 v31, 0xffff0000, v153
	v_pk_fma_f32 v[22:23], v[22:23], 0.5, v[30:31] op_sel_hi:[1,0,1]
	v_pk_fma_f32 v[20:21], v[20:21], 0.5, v[24:25] op_sel_hi:[1,0,1]
	v_mul_f32_e32 v25, v23, v23
	v_mul_f32_e32 v24, v21, v21
	v_fmac_f32_e32 v24, v20, v20
	v_fmac_f32_e32 v25, v22, v22
	v_add_f32_e32 v24, v24, v25
	v_add_f32_e32 v29, v29, v24
	v_lshlrev_b32_e32 v24, 16, v154
	v_and_b32_e32 v25, 0xffff0000, v154
	v_lshlrev_b32_e32 v30, 16, v155
	v_and_b32_e32 v31, 0xffff0000, v155
	v_pk_fma_f32 v[18:19], v[18:19], 0.5, v[30:31] op_sel_hi:[1,0,1]
	v_pk_fma_f32 v[24:25], v[16:17], 0.5, v[24:25] op_sel_hi:[1,0,1]
	v_mul_f32_e32 v17, v19, v19
	v_mul_f32_e32 v16, v25, v25
	v_fmac_f32_e32 v16, v24, v24
	v_fmac_f32_e32 v17, v18, v18
	v_add_f32_e32 v16, v16, v17
	v_add_f32_e32 v16, v29, v16
	v_mov_b32_e32 v17, v16
	s_nop 1
	v_permlane16_swap_b32_e32 v16, v17
	v_cvt_pk_bf16_f32 v30, v20, v21
	v_cvt_pk_bf16_f32 v31, v22, v23
	v_cvt_pk_bf16_f32 v39, v26, v27
	s_waitcnt lgkmcnt(0)
	v_add_f32_e32 v16, v16, v17
	v_mov_b32_e32 v17, v16
	s_nop 1
	v_permlane32_swap_b32_e32 v16, v17
	v_cvt_pk_bf16_f32 v32, v24, v25
	v_cvt_pk_bf16_f32 v33, v18, v19
	v_lshl_add_u64 v[34:35], v[34:35], 0, v[250:251]
	s_nop 1
	v_permlane16_swap_b32_e32 v36, v38
	v_permlane16_swap_b32_e32 v37, v39
	global_store_dwordx4 v[34:35], v[36:39], off
	s_nop 1
	s_nop 1
	v_permlane16_swap_b32_e32 v30, v32
	v_permlane16_swap_b32_e32 v31, v33
	global_store_dwordx4 v[34:35], v[30:33], off offset:256
	s_nop 1
	s_and_saveexec_b64 s[36:37], vcc
	s_cbranch_execz .LBB0_785
	v_lshlrev_b64 v[18:19], 6, v[148:149]
	v_lshl_add_u64 v[18:19], s[18:19], 0, v[18:19]
	v_lshl_add_u64 v[18:19], s[34:35], 2, v[18:19]
	s_lshl_b32 s12, s48, 2
	v_lshl_add_u64 v[18:19], v[18:19], 0, s[12:13]
	s_waitcnt lgkmcnt(0)
	v_add_f32_e32 v16, v16, v17
	global_store_dword v[18:19], v16, off
.LBB0_785:
	s_or_b64 exec, exec, s[36:37]
	s_waitcnt vmcnt(16)
	v_permlane16_swap_b32_e32 v144, v146
	v_permlane16_swap_b32_e32 v145, v147
	v_permlane16_swap_b32_e32 v140, v142
	v_permlane16_swap_b32_e32 v141, v143
	v_lshlrev_b64 v[150:151], 11, v[136:137]
	v_lshlrev_b32_e32 v16, 16, v144
	s_waitcnt lgkmcnt(0)
	v_and_b32_e32 v17, 0xffff0000, v144
	v_lshlrev_b32_e32 v18, 16, v145
	v_and_b32_e32 v19, 0xffff0000, v145
	v_pk_fma_f32 v[12:13], v[12:13], 0.5, v[16:17] op_sel_hi:[1,0,1]
	v_pk_fma_f32 v[14:15], v[14:15], 0.5, v[18:19] op_sel_hi:[1,0,1]
	v_cvt_pk_bf16_f32 v20, v12, v13
	v_mul_f32_e32 v13, v13, v13
	v_lshl_add_u64 v[18:19], s[16:17], 0, v[150:151]
	v_fmac_f32_e32 v13, v12, v12
	v_mul_f32_e32 v12, v15, v15
	v_cvt_pk_bf16_f32 v21, v14, v15
	v_lshl_add_u64 v[18:19], v[138:139], 1, v[18:19]
	v_fmac_f32_e32 v12, v14, v14
	v_add_f32_e32 v16, v13, v12
	v_lshlrev_b32_e32 v12, 16, v146
	v_and_b32_e32 v13, 0xffff0000, v146
	v_lshlrev_b32_e32 v14, 16, v147
	v_and_b32_e32 v15, 0xffff0000, v147
	v_pk_fma_f32 v[8:9], v[8:9], 0.5, v[12:13] op_sel_hi:[1,0,1]
	v_pk_fma_f32 v[10:11], v[10:11], 0.5, v[14:15] op_sel_hi:[1,0,1]
	v_cvt_pk_bf16_f32 v22, v8, v9
	v_mul_f32_e32 v9, v9, v9
	v_fmac_f32_e32 v9, v8, v8
	v_mul_f32_e32 v8, v11, v11
	v_fmac_f32_e32 v8, v10, v10
	v_add_f32_e32 v8, v9, v8
	v_add_f32_e32 v13, v16, v8
	v_lshlrev_b32_e32 v8, 16, v140
	v_and_b32_e32 v9, 0xffff0000, v140
	v_lshlrev_b32_e32 v14, 16, v141
	v_and_b32_e32 v15, 0xffff0000, v141
	v_pk_fma_f32 v[6:7], v[6:7], 0.5, v[14:15] op_sel_hi:[1,0,1]
	v_pk_fma_f32 v[4:5], v[4:5], 0.5, v[8:9] op_sel_hi:[1,0,1]
	v_mul_f32_e32 v9, v7, v7
	v_mul_f32_e32 v8, v5, v5
	v_fmac_f32_e32 v8, v4, v4
	v_fmac_f32_e32 v9, v6, v6
	v_add_f32_e32 v8, v8, v9
	v_add_f32_e32 v13, v13, v8
	v_lshlrev_b32_e32 v8, 16, v142
	v_and_b32_e32 v9, 0xffff0000, v142
	v_lshlrev_b32_e32 v14, 16, v143
	v_and_b32_e32 v15, 0xffff0000, v143
	v_pk_fma_f32 v[2:3], v[2:3], 0.5, v[14:15] op_sel_hi:[1,0,1]
	v_pk_fma_f32 v[8:9], v[0:1], 0.5, v[8:9] op_sel_hi:[1,0,1]
	v_mul_f32_e32 v1, v3, v3
	v_mul_f32_e32 v0, v9, v9
	v_fmac_f32_e32 v0, v8, v8
	v_fmac_f32_e32 v1, v2, v2
	v_add_f32_e32 v0, v0, v1
	v_add_f32_e32 v0, v13, v0
	v_mov_b32_e32 v1, v0
	s_nop 1
	v_permlane16_swap_b32_e32 v0, v1
	v_cvt_pk_bf16_f32 v14, v4, v5
	v_cvt_pk_bf16_f32 v15, v6, v7
	v_cvt_pk_bf16_f32 v23, v10, v11
	s_waitcnt lgkmcnt(0)
	v_add_f32_e32 v0, v0, v1
	v_mov_b32_e32 v1, v0
	s_nop 1
	v_permlane32_swap_b32_e32 v0, v1
	v_cvt_pk_bf16_f32 v16, v8, v9
	v_cvt_pk_bf16_f32 v17, v2, v3
	v_lshl_add_u64 v[18:19], v[18:19], 0, v[250:251]
	s_nop 1
	v_permlane16_swap_b32_e32 v20, v22
	v_permlane16_swap_b32_e32 v21, v23
	global_store_dwordx4 v[18:19], v[20:23], off
	s_nop 1
	s_nop 1
	v_permlane16_swap_b32_e32 v14, v16
	v_permlane16_swap_b32_e32 v15, v17
	global_store_dwordx4 v[18:19], v[14:17], off offset:256
	s_nop 1
	s_and_saveexec_b64 s[36:37], vcc
	s_cbranch_execz .LBB0_787
	v_lshlrev_b64 v[2:3], 6, v[136:137]
	v_lshl_add_u64 v[2:3], s[18:19], 0, v[2:3]
	v_lshl_add_u64 v[2:3], s[34:35], 2, v[2:3]
	s_lshl_b32 s12, s48, 2
	v_lshl_add_u64 v[2:3], v[2:3], 0, s[12:13]
	s_waitcnt lgkmcnt(0)
	v_add_f32_e32 v0, v0, v1
	global_store_dword v[2:3], v0, off

; #define PG8_GAS __attribute__((address_space(1)))
; __device__ __forceinline__ unsigned pk2_(float lo, float hi) { f32x2c_t v = {lo, hi}; bf16x2c_t b = __builtin_convertvector(v, bf16x2c_t); return __builtin_bit_cast(unsigned, b); }
;     __device__ __forceinline__ void operator()(const f32x4 (&acc)[2][2][4][2], const Unit& u, int wr, int wc, int fr, int fq) const {
;     ...
;         const int row0 = u.pm * BM + wr * 64 + fr, col0 = u.pn * BM + wc * 32 + 4 * fq;
;         u32x2v bsv[2][4][2][2];
; #pragma unroll
;         for (int ai = 0; ai < 2; ++ai)
; #pragma unroll
;             for (int m = 0; m < 4; ++m) { const size_t off = (size_t)(row0 + ai * HALF + m * 16) * 1024 + col0;
; #pragma unroll
;                 for (int bj = 0; bj < 2; ++bj)
; #pragma unroll
;                     for (int n = 0; n < 2; ++n) bsv[ai][m][bj][n] = *(const PG8_GAS u32x2v*)(hbase + off + bj * HALF + n * 16); }
; #pragma unroll
;         for (int ai = 0; ai < 2; ++ai)
; #pragma unroll
;             for (int m = 0; m < 4; ++m) {
;                 const int r = row0 + ai * HALF + m * 16; const size_t off = (size_t)r * 1024 + col0; float ss = 0.f;
; #pragma unroll
;                 for (int bj = 0; bj < 2; ++bj)
; #pragma unroll
;                     for (int n = 0; n < 2; ++n) {
;                         const u32x2v w0 = bsv[ai][m][bj][n]; f32x4 bs;
;                         bs[0] = __builtin_bit_cast(float, w0.x << 16); bs[1] = __builtin_bit_cast(float, w0.x & 0xffff0000u); bs[2] = __builtin_bit_cast(float, w0.y << 16); bs[3] = __builtin_bit_cast(float, w0.y & 0xffff0000u);
;                         const f32x4 v = bs + acc[ai][bj][m][n] * alpha;
;                         { u32x2v w; w.x = pk2_(v[0], v[1]); w.y = pk2_(v[2], v[3]); *(PG8_GAS u32x2v*)(hb + off + bj * HALF + n * 16) = w; }
;                         ss += (v[0] * v[0] + v[1] * v[1]) + (v[2] * v[2] + v[3] * v[3]);
;                     }
;                 ss += __shfl_xor(ss, 16); ss += __shfl_xor(ss, 32);
;                 if (fq == 0) ((PG8_GAS float*)parts)[(size_t)r * 16 + u.pn * 4 + wc] = ss;
;             }
.LBB0_1378:
	s_lshl_b32 s27, s36, 8
	v_mov_b32_e32 v136, v252
	s_add_i32 s27, s27, s54
	v_cmp_lt_i32_e32 vcc, v227, v226
	v_and_or_b32 v220, v136, 15, s27
	s_lshl_b32 s27, s10, 8
	v_bfe_u32 v244, v136, 4, 2
	s_or_b32 s27, s27, s55
	v_lshl_or_b32 v138, v244, 2, s27
	v_ashrrev_i32_e32 v139, 31, v138
	v_lshlrev_b64 v[224:225], 1, v[138:139]
	v_ashrrev_i32_e32 v221, 31, v220
	v_lshl_add_u64 v[140:141], s[12:13], 0, v[224:225]
	v_lshlrev_b64 v[234:235], 11, v[220:221]
	v_lshl_add_u64 v[136:137], v[140:141], 0, v[234:235]
	v_bfe_u32 v250, v252, 4, 1
	v_mul_u32_u24_e32 v250, 24, v250
	v_mov_b32_e32 v251, 0
	v_lshl_add_u64 v[136:137], v[136:137], 0, v[250:251]
	global_load_dwordx4 v[236:239], v[136:137], off
	global_load_dwordx4 v[240:243], v[136:137], off offset:256
	v_or_b32_e32 v208, 16, v220
	v_ashrrev_i32_e32 v209, 31, v208
	v_or_b32_e32 v196, 32, v220
	v_lshlrev_b64 v[218:219], 11, v[208:209]
	v_ashrrev_i32_e32 v197, 31, v196
	v_or_b32_e32 v184, 48, v220
	v_lshl_add_u64 v[136:137], v[140:141], 0, v[218:219]
	v_lshlrev_b64 v[206:207], 11, v[196:197]
	v_ashrrev_i32_e32 v185, 31, v184
	v_add_u32_e32 v172, 0x80, v220
	v_lshl_add_u64 v[136:137], v[136:137], 0, v[250:251]
	global_load_dwordx4 v[216:219], v[136:137], off
	global_load_dwordx4 v[212:215], v[136:137], off offset:256
	v_lshl_add_u64 v[136:137], v[140:141], 0, v[206:207]
	v_lshlrev_b64 v[194:195], 11, v[184:185]
	v_ashrrev_i32_e32 v173, 31, v172
	v_add_u32_e32 v160, 0x90, v220
	v_lshl_add_u64 v[136:137], v[136:137], 0, v[250:251]
	global_load_dwordx4 v[204:207], v[136:137], off
	global_load_dwordx4 v[200:203], v[136:137], off offset:256
	v_lshl_add_u64 v[136:137], v[140:141], 0, v[194:195]
	v_lshlrev_b64 v[182:183], 11, v[172:173]
	v_ashrrev_i32_e32 v161, 31, v160
	v_add_u32_e32 v148, 0xa0, v220
	v_lshl_add_u64 v[136:137], v[136:137], 0, v[250:251]
	global_load_dwordx4 v[192:195], v[136:137], off
	global_load_dwordx4 v[188:191], v[136:137], off offset:256
	v_lshl_add_u64 v[136:137], v[140:141], 0, v[182:183]
	v_lshlrev_b64 v[170:171], 11, v[160:161]
	v_ashrrev_i32_e32 v149, 31, v148
	v_lshl_add_u64 v[136:137], v[136:137], 0, v[250:251]
	global_load_dwordx4 v[180:183], v[136:137], off
	global_load_dwordx4 v[176:179], v[136:137], off offset:256
	v_lshl_add_u64 v[136:137], v[140:141], 0, v[170:171]
	v_lshlrev_b64 v[158:159], 11, v[148:149]
	v_lshl_add_u64 v[136:137], v[136:137], 0, v[250:251]
	global_load_dwordx4 v[168:171], v[136:137], off
	global_load_dwordx4 v[164:167], v[136:137], off offset:256
	v_lshl_add_u64 v[136:137], v[140:141], 0, v[158:159]
	v_lshl_add_u64 v[136:137], v[136:137], 0, v[250:251]
	global_load_dwordx4 v[156:159], v[136:137], off
	global_load_dwordx4 v[152:155], v[136:137], off offset:256
	v_add_u32_e32 v136, 0xb0, v220
	v_ashrrev_i32_e32 v137, 31, v136
	v_lshlrev_b64 v[146:147], 11, v[136:137]
	v_lshl_add_u64 v[140:141], v[140:141], 0, v[146:147]
	v_lshl_add_u64 v[140:141], v[140:141], 0, v[250:251]
	global_load_dwordx4 v[144:147], v[140:141], off
	global_load_dwordx4 v[140:143], v[140:141], off offset:256
	s_nop 0
	v_xor_b32_e32 v245, 32, v253
	v_cndmask_b32_e32 v232, v253, v227, vcc
	v_cmp_lt_i32_e32 vcc, v245, v226
	v_lshlrev_b32_e32 v233, 2, v232
	v_lshl_add_u64 v[234:235], s[12:13], 0, v[234:235]
	v_cndmask_b32_e32 v232, v253, v245, vcc
	v_cmp_eq_u32_e32 vcc, 0, v244
	v_lshl_add_u64 v[224:225], v[234:235], 0, v[224:225]
	v_lshlrev_b32_e32 v232, 2, v232
	s_lshl_b32 s36, s10, 2
	s_ashr_i32 s37, s36, 31
	s_waitcnt vmcnt(14)
	v_permlane16_swap_b32_e32 v236, v238
	v_permlane16_swap_b32_e32 v237, v239
	v_permlane16_swap_b32_e32 v240, v242
	v_permlane16_swap_b32_e32 v241, v243
	v_lshlrev_b32_e32 v244, 16, v236
	v_and_b32_e32 v245, 0xffff0000, v236
	v_lshlrev_b32_e32 v236, 16, v237
	v_and_b32_e32 v237, 0xffff0000, v237
	v_pk_add_f32 v[124:125], v[124:125], v[244:245]
	v_pk_add_f32 v[126:127], v[126:127], v[236:237]
	v_cvt_pk_bf16_f32 v236, v124, v125
	v_mul_f32_e32 v125, v125, v125
	v_fmac_f32_e32 v125, v124, v124
	v_mul_f32_e32 v124, v127, v127
	v_fmac_f32_e32 v124, v126, v126
	v_add_f32_e32 v234, v125, v124
	v_lshlrev_b32_e32 v124, 16, v238
	v_and_b32_e32 v125, 0xffff0000, v238
	v_cvt_pk_bf16_f32 v237, v126, v127
	v_lshlrev_b32_e32 v126, 16, v239
	v_and_b32_e32 v127, 0xffff0000, v239
	v_pk_add_f32 v[120:121], v[120:121], v[124:125]
	v_pk_add_f32 v[122:123], v[122:123], v[126:127]
	v_cvt_pk_bf16_f32 v124, v120, v121
	v_mul_f32_e32 v121, v121, v121
	v_fmac_f32_e32 v121, v120, v120
	v_mul_f32_e32 v120, v123, v123
	v_fmac_f32_e32 v120, v122, v122
	v_add_f32_e32 v120, v121, v120
	v_add_f32_e32 v125, v234, v120
	v_lshlrev_b32_e32 v120, 16, v240
	v_and_b32_e32 v121, 0xffff0000, v240
	v_lshlrev_b32_e32 v126, 16, v241
	v_and_b32_e32 v127, 0xffff0000, v241
	v_pk_add_f32 v[118:119], v[118:119], v[126:127]
	v_pk_add_f32 v[116:117], v[116:117], v[120:121]
	v_mul_f32_e32 v121, v119, v119
	v_mul_f32_e32 v120, v117, v117
	v_fmac_f32_e32 v120, v116, v116
	v_fmac_f32_e32 v121, v118, v118
	v_add_f32_e32 v120, v120, v121
	v_add_f32_e32 v125, v125, v120
	v_lshlrev_b32_e32 v120, 16, v242
	v_and_b32_e32 v121, 0xffff0000, v242
	v_lshlrev_b32_e32 v126, 16, v243
	v_and_b32_e32 v127, 0xffff0000, v243
	v_pk_add_f32 v[114:115], v[114:115], v[126:127]
	v_pk_add_f32 v[120:121], v[112:113], v[120:121]
	v_mul_f32_e32 v113, v115, v115
	v_mul_f32_e32 v112, v121, v121
	v_fmac_f32_e32 v112, v120, v120
	v_fmac_f32_e32 v113, v114, v114
	v_add_f32_e32 v112, v112, v113
	v_add_f32_e32 v112, v125, v112
	v_mov_b32_e32 v113, v112
	s_nop 1
	v_permlane16_swap_b32_e32 v112, v113
	v_cvt_pk_bf16_f32 v116, v116, v117
	v_cvt_pk_bf16_f32 v117, v118, v119
	v_cvt_pk_bf16_f32 v125, v122, v123
	global_store_dwordx2 v[224:225], v[116:117], off offset:256
	s_waitcnt lgkmcnt(0)
	v_add_f32_e32 v112, v112, v113
	v_mov_b32_e32 v113, v112
	s_nop 1
	v_permlane32_swap_b32_e32 v112, v113
	v_cvt_pk_bf16_f32 v116, v120, v121
	v_cvt_pk_bf16_f32 v117, v114, v115
	global_store_dwordx2 v[224:225], v[236:237], off
	global_store_dwordx2 v[224:225], v[124:125], off offset:32
	global_store_dwordx2 v[224:225], v[116:117], off offset:288
	s_and_saveexec_b64 s[38:39], vcc
	s_cbranch_execz .LBB0_1380
	v_lshlrev_b64 v[114:115], 6, v[220:221]
	v_lshl_add_u64 v[114:115], s[14:15], 0, v[114:115]
	v_lshl_add_u64 v[114:115], s[36:37], 2, v[114:115]
	s_lshl_b32 s10, s53, 2
	v_lshl_add_u64 v[114:115], v[114:115], 0, s[10:11]
	s_waitcnt lgkmcnt(0)
	v_add_f32_e32 v112, v112, v113
	global_store_dword v[114:115], v112, off
; #define PG8_GAS __attribute__((address_space(1)))
; __device__ __forceinline__ unsigned pk2_(float lo, float hi) { f32x2c_t v = {lo, hi}; bf16x2c_t b = __builtin_convertvector(v, bf16x2c_t); return __builtin_bit_cast(unsigned, b); }
;     __device__ __forceinline__ void operator()(const f32x4 (&acc)[2][2][4][2], const Unit& u, int wr, int wc, int fr, int fq) const {
;     ...
;         for (int ai = 0; ai < 2; ++ai)
; #pragma unroll
;             for (int m = 0; m < 4; ++m) {
;                 const int r = row0 + ai * HALF + m * 16; const size_t off = (size_t)r * 1024 + col0; float ss = 0.f;
; #pragma unroll
;                 for (int bj = 0; bj < 2; ++bj)
; #pragma unroll
;                     for (int n = 0; n < 2; ++n) {
;                         const u32x2v w0 = bsv[ai][m][bj][n]; f32x4 bs;
;                         bs[0] = __builtin_bit_cast(float, w0.x << 16); bs[1] = __builtin_bit_cast(float, w0.x & 0xffff0000u); bs[2] = __builtin_bit_cast(float, w0.y << 16); bs[3] = __builtin_bit_cast(float, w0.y & 0xffff0000u);
;                         const f32x4 v = bs + acc[ai][bj][m][n] * alpha;
;                         { u32x2v w; w.x = pk2_(v[0], v[1]); w.y = pk2_(v[2], v[3]); *(PG8_GAS u32x2v*)(hb + off + bj * HALF + n * 16) = w; }
;                         ss += (v[0] * v[0] + v[1] * v[1]) + (v[2] * v[2] + v[3] * v[3]);
;                     }
;                 ss += __shfl_xor(ss, 16); ss += __shfl_xor(ss, 32);
;                 if (fq == 0) ((PG8_GAS float*)parts)[(size_t)r * 16 + u.pn * 4 + wc] = ss;
;             }
.LBB0_1380:
	s_or_b64 exec, exec, s[38:39]
	s_waitcnt vmcnt(16)
	v_permlane16_swap_b32_e32 v216, v218
	v_permlane16_swap_b32_e32 v217, v219
	v_permlane16_swap_b32_e32 v212, v214
	v_permlane16_swap_b32_e32 v213, v215
	v_lshlrev_b64 v[222:223], 11, v[208:209]
	v_lshlrev_b32_e32 v112, 16, v216
	s_waitcnt lgkmcnt(0)
	v_and_b32_e32 v113, 0xffff0000, v216
	v_lshlrev_b32_e32 v114, 16, v217
	v_and_b32_e32 v115, 0xffff0000, v217
	v_pk_add_f32 v[108:109], v[108:109], v[112:113]
	v_pk_add_f32 v[110:111], v[110:111], v[114:115]
	v_cvt_pk_bf16_f32 v116, v108, v109
	v_mul_f32_e32 v109, v109, v109
	v_lshl_add_u64 v[114:115], s[12:13], 0, v[222:223]
	v_fmac_f32_e32 v109, v108, v108
	v_mul_f32_e32 v108, v111, v111
	v_cvt_pk_bf16_f32 v117, v110, v111
	v_lshl_add_u64 v[114:115], v[138:139], 1, v[114:115]
	v_fmac_f32_e32 v108, v110, v110
	v_add_f32_e32 v112, v109, v108
	v_lshlrev_b32_e32 v108, 16, v218
	v_and_b32_e32 v109, 0xffff0000, v218
	v_lshlrev_b32_e32 v110, 16, v219
	v_and_b32_e32 v111, 0xffff0000, v219
	v_pk_add_f32 v[104:105], v[104:105], v[108:109]
	v_pk_add_f32 v[106:107], v[106:107], v[110:111]
	v_cvt_pk_bf16_f32 v118, v104, v105
	v_mul_f32_e32 v105, v105, v105
	v_fmac_f32_e32 v105, v104, v104
	v_mul_f32_e32 v104, v107, v107
	v_fmac_f32_e32 v104, v106, v106
	v_add_f32_e32 v104, v105, v104
	v_add_f32_e32 v109, v112, v104
	v_lshlrev_b32_e32 v104, 16, v212
	v_and_b32_e32 v105, 0xffff0000, v212
	v_lshlrev_b32_e32 v110, 16, v213
	v_and_b32_e32 v111, 0xffff0000, v213
	v_pk_add_f32 v[102:103], v[102:103], v[110:111]
	v_pk_add_f32 v[100:101], v[100:101], v[104:105]
	v_mul_f32_e32 v105, v103, v103
	v_mul_f32_e32 v104, v101, v101
	v_fmac_f32_e32 v104, v100, v100
	v_fmac_f32_e32 v105, v102, v102
	v_add_f32_e32 v104, v104, v105
	v_add_f32_e32 v109, v109, v104
	v_lshlrev_b32_e32 v104, 16, v214
	v_and_b32_e32 v105, 0xffff0000, v214
	v_lshlrev_b32_e32 v110, 16, v215
	v_and_b32_e32 v111, 0xffff0000, v215
	v_pk_add_f32 v[98:99], v[98:99], v[110:111]
	v_pk_add_f32 v[104:105], v[96:97], v[104:105]
	v_mul_f32_e32 v97, v99, v99
	v_mul_f32_e32 v96, v105, v105
	v_fmac_f32_e32 v96, v104, v104
	v_fmac_f32_e32 v97, v98, v98
	v_add_f32_e32 v96, v96, v97
	v_add_f32_e32 v96, v109, v96
	v_mov_b32_e32 v97, v96
	s_nop 1
	v_permlane16_swap_b32_e32 v96, v97
	v_cvt_pk_bf16_f32 v110, v100, v101
	v_cvt_pk_bf16_f32 v111, v102, v103
	v_cvt_pk_bf16_f32 v119, v106, v107
	s_waitcnt lgkmcnt(0)
	v_add_f32_e32 v96, v96, v97
	v_mov_b32_e32 v97, v96
	s_nop 1
	v_permlane32_swap_b32_e32 v96, v97
	v_cvt_pk_bf16_f32 v112, v104, v105
	v_cvt_pk_bf16_f32 v113, v98, v99
	v_lshl_add_u64 v[114:115], v[114:115], 0, v[250:251]
	s_nop 1
	v_permlane16_swap_b32_e32 v116, v118
	v_permlane16_swap_b32_e32 v117, v119
	global_store_dwordx4 v[114:115], v[116:119], off
	s_nop 1
	s_nop 1
	v_permlane16_swap_b32_e32 v110, v112
	v_permlane16_swap_b32_e32 v111, v113
	global_store_dwordx4 v[114:115], v[110:113], off offset:256
	s_nop 1
	s_and_saveexec_b64 s[38:39], vcc
	s_cbranch_execz .LBB0_1382
	v_lshlrev_b64 v[98:99], 6, v[208:209]
	v_lshl_add_u64 v[98:99], s[14:15], 0, v[98:99]
	v_lshl_add_u64 v[98:99], s[36:37], 2, v[98:99]
	s_lshl_b32 s10, s53, 2
	v_lshl_add_u64 v[98:99], v[98:99], 0, s[10:11]
	s_waitcnt lgkmcnt(0)
	v_add_f32_e32 v96, v96, v97
	global_store_dword v[98:99], v96, off
.LBB0_1382:
	s_or_b64 exec, exec, s[38:39]
	s_waitcnt vmcnt(16)
	v_permlane16_swap_b32_e32 v204, v206
	v_permlane16_swap_b32_e32 v205, v207
	v_permlane16_swap_b32_e32 v200, v202
	v_permlane16_swap_b32_e32 v201, v203
	v_lshlrev_b64 v[210:211], 11, v[196:197]
	v_lshlrev_b32_e32 v96, 16, v204
	s_waitcnt lgkmcnt(0)
	v_and_b32_e32 v97, 0xffff0000, v204
	v_lshlrev_b32_e32 v98, 16, v205
	v_and_b32_e32 v99, 0xffff0000, v205
	v_pk_add_f32 v[92:93], v[92:93], v[96:97]
	v_pk_add_f32 v[94:95], v[94:95], v[98:99]
	v_cvt_pk_bf16_f32 v100, v92, v93
	v_mul_f32_e32 v93, v93, v93
	v_lshl_add_u64 v[98:99], s[12:13], 0, v[210:211]
	v_fmac_f32_e32 v93, v92, v92
	v_mul_f32_e32 v92, v95, v95
	v_cvt_pk_bf16_f32 v101, v94, v95
	v_lshl_add_u64 v[98:99], v[138:139], 1, v[98:99]
	v_fmac_f32_e32 v92, v94, v94
	v_add_f32_e32 v96, v93, v92
	v_lshlrev_b32_e32 v92, 16, v206
	v_and_b32_e32 v93, 0xffff0000, v206
	v_lshlrev_b32_e32 v94, 16, v207
	v_and_b32_e32 v95, 0xffff0000, v207
	v_pk_add_f32 v[88:89], v[88:89], v[92:93]
	v_pk_add_f32 v[90:91], v[90:91], v[94:95]
	v_cvt_pk_bf16_f32 v102, v88, v89
	v_mul_f32_e32 v89, v89, v89
	v_fmac_f32_e32 v89, v88, v88
	v_mul_f32_e32 v88, v91, v91
	v_fmac_f32_e32 v88, v90, v90
	v_add_f32_e32 v88, v89, v88
	v_add_f32_e32 v93, v96, v88
	v_lshlrev_b32_e32 v88, 16, v200
	v_and_b32_e32 v89, 0xffff0000, v200
	v_lshlrev_b32_e32 v94, 16, v201
	v_and_b32_e32 v95, 0xffff0000, v201
	v_pk_add_f32 v[86:87], v[86:87], v[94:95]
	v_pk_add_f32 v[84:85], v[84:85], v[88:89]
	v_mul_f32_e32 v89, v87, v87
	v_mul_f32_e32 v88, v85, v85
	v_fmac_f32_e32 v88, v84, v84
	v_fmac_f32_e32 v89, v86, v86
	v_add_f32_e32 v88, v88, v89
	v_add_f32_e32 v93, v93, v88
	v_lshlrev_b32_e32 v88, 16, v202
	v_and_b32_e32 v89, 0xffff0000, v202
	v_lshlrev_b32_e32 v94, 16, v203
	v_and_b32_e32 v95, 0xffff0000, v203
	v_pk_add_f32 v[82:83], v[82:83], v[94:95]
	v_pk_add_f32 v[88:89], v[80:81], v[88:89]
	v_mul_f32_e32 v81, v83, v83
	v_mul_f32_e32 v80, v89, v89
	v_fmac_f32_e32 v80, v88, v88
	v_fmac_f32_e32 v81, v82, v82
	v_add_f32_e32 v80, v80, v81
	v_add_f32_e32 v80, v93, v80
	v_mov_b32_e32 v81, v80
	s_nop 1
	v_permlane16_swap_b32_e32 v80, v81
	v_cvt_pk_bf16_f32 v94, v84, v85
	v_cvt_pk_bf16_f32 v95, v86, v87
	v_cvt_pk_bf16_f32 v103, v90, v91
	s_waitcnt lgkmcnt(0)
	v_add_f32_e32 v80, v80, v81
	v_mov_b32_e32 v81, v80
	s_nop 1
	v_permlane32_swap_b32_e32 v80, v81
	v_cvt_pk_bf16_f32 v96, v88, v89
	v_cvt_pk_bf16_f32 v97, v82, v83
	v_lshl_add_u64 v[98:99], v[98:99], 0, v[250:251]
	s_nop 1
	v_permlane16_swap_b32_e32 v100, v102
	v_permlane16_swap_b32_e32 v101, v103
	global_store_dwordx4 v[98:99], v[100:103], off
	s_nop 1
	s_nop 1
	v_permlane16_swap_b32_e32 v94, v96
	v_permlane16_swap_b32_e32 v95, v97
	global_store_dwordx4 v[98:99], v[94:97], off offset:256
	s_nop 1
	s_and_saveexec_b64 s[38:39], vcc
	s_cbranch_execz .LBB0_1384
	v_lshlrev_b64 v[82:83], 6, v[196:197]
	v_lshl_add_u64 v[82:83], s[14:15], 0, v[82:83]
	v_lshl_add_u64 v[82:83], s[36:37], 2, v[82:83]
	s_lshl_b32 s10, s53, 2
	v_lshl_add_u64 v[82:83], v[82:83], 0, s[10:11]
	s_waitcnt lgkmcnt(0)
	v_add_f32_e32 v80, v80, v81
	global_store_dword v[82:83], v80, off
; #define PG8_GAS __attribute__((address_space(1)))
; __device__ __forceinline__ unsigned pk2_(float lo, float hi) { f32x2c_t v = {lo, hi}; bf16x2c_t b = __builtin_convertvector(v, bf16x2c_t); return __builtin_bit_cast(unsigned, b); }
;     __device__ __forceinline__ void operator()(const f32x4 (&acc)[2][2][4][2], const Unit& u, int wr, int wc, int fr, int fq) const {
;     ...
;         for (int ai = 0; ai < 2; ++ai)
; #pragma unroll
;             for (int m = 0; m < 4; ++m) {
;                 const int r = row0 + ai * HALF + m * 16; const size_t off = (size_t)r * 1024 + col0; float ss = 0.f;
; #pragma unroll
;                 for (int bj = 0; bj < 2; ++bj)
; #pragma unroll
;                     for (int n = 0; n < 2; ++n) {
;                         const u32x2v w0 = bsv[ai][m][bj][n]; f32x4 bs;
;                         bs[0] = __builtin_bit_cast(float, w0.x << 16); bs[1] = __builtin_bit_cast(float, w0.x & 0xffff0000u); bs[2] = __builtin_bit_cast(float, w0.y << 16); bs[3] = __builtin_bit_cast(float, w0.y & 0xffff0000u);
;                         const f32x4 v = bs + acc[ai][bj][m][n] * alpha;
;                         { u32x2v w; w.x = pk2_(v[0], v[1]); w.y = pk2_(v[2], v[3]); *(PG8_GAS u32x2v*)(hb + off + bj * HALF + n * 16) = w; }
;                         ss += (v[0] * v[0] + v[1] * v[1]) + (v[2] * v[2] + v[3] * v[3]);
;                     }
;                 ss += __shfl_xor(ss, 16); ss += __shfl_xor(ss, 32);
;                 if (fq == 0) ((PG8_GAS float*)parts)[(size_t)r * 16 + u.pn * 4 + wc] = ss;
;             }
.LBB0_1384:
	s_or_b64 exec, exec, s[38:39]
	s_waitcnt vmcnt(16)
	v_permlane16_swap_b32_e32 v192, v194
	v_permlane16_swap_b32_e32 v193, v195
	v_permlane16_swap_b32_e32 v188, v190
	v_permlane16_swap_b32_e32 v189, v191
	v_lshlrev_b64 v[198:199], 11, v[184:185]
	v_lshlrev_b32_e32 v80, 16, v192
	s_waitcnt lgkmcnt(0)
	v_and_b32_e32 v81, 0xffff0000, v192
	v_lshlrev_b32_e32 v82, 16, v193
	v_and_b32_e32 v83, 0xffff0000, v193
	v_pk_add_f32 v[76:77], v[76:77], v[80:81]
	v_pk_add_f32 v[78:79], v[78:79], v[82:83]
	v_cvt_pk_bf16_f32 v84, v76, v77
	v_mul_f32_e32 v77, v77, v77
	v_lshl_add_u64 v[82:83], s[12:13], 0, v[198:199]
	v_fmac_f32_e32 v77, v76, v76
	v_mul_f32_e32 v76, v79, v79
	v_cvt_pk_bf16_f32 v85, v78, v79
	v_lshl_add_u64 v[82:83], v[138:139], 1, v[82:83]
	v_fmac_f32_e32 v76, v78, v78
	v_add_f32_e32 v80, v77, v76
	v_lshlrev_b32_e32 v76, 16, v194
	v_and_b32_e32 v77, 0xffff0000, v194
	v_lshlrev_b32_e32 v78, 16, v195
	v_and_b32_e32 v79, 0xffff0000, v195
	v_pk_add_f32 v[72:73], v[72:73], v[76:77]
	v_pk_add_f32 v[74:75], v[74:75], v[78:79]
	v_cvt_pk_bf16_f32 v86, v72, v73
	v_mul_f32_e32 v73, v73, v73
	v_fmac_f32_e32 v73, v72, v72
	v_mul_f32_e32 v72, v75, v75
	v_fmac_f32_e32 v72, v74, v74
	v_add_f32_e32 v72, v73, v72
	v_add_f32_e32 v77, v80, v72
	v_lshlrev_b32_e32 v72, 16, v188
	v_and_b32_e32 v73, 0xffff0000, v188
	v_lshlrev_b32_e32 v78, 16, v189
	v_and_b32_e32 v79, 0xffff0000, v189
	v_pk_add_f32 v[70:71], v[70:71], v[78:79]
	v_pk_add_f32 v[68:69], v[68:69], v[72:73]
	v_mul_f32_e32 v73, v71, v71
	v_mul_f32_e32 v72, v69, v69
	v_fmac_f32_e32 v72, v68, v68
	v_fmac_f32_e32 v73, v70, v70
	v_add_f32_e32 v72, v72, v73
	v_add_f32_e32 v77, v77, v72
	v_lshlrev_b32_e32 v72, 16, v190
	v_and_b32_e32 v73, 0xffff0000, v190
	v_lshlrev_b32_e32 v78, 16, v191
	v_and_b32_e32 v79, 0xffff0000, v191
	v_pk_add_f32 v[66:67], v[66:67], v[78:79]
	v_pk_add_f32 v[72:73], v[64:65], v[72:73]
	v_mul_f32_e32 v65, v67, v67
	v_mul_f32_e32 v64, v73, v73
	v_fmac_f32_e32 v64, v72, v72
	v_fmac_f32_e32 v65, v66, v66
	v_add_f32_e32 v64, v64, v65
	v_add_f32_e32 v64, v77, v64
	v_mov_b32_e32 v65, v64
	s_nop 1
	v_permlane16_swap_b32_e32 v64, v65
	v_cvt_pk_bf16_f32 v78, v68, v69
	v_cvt_pk_bf16_f32 v79, v70, v71
	v_cvt_pk_bf16_f32 v87, v74, v75
	s_waitcnt lgkmcnt(0)
	v_add_f32_e32 v64, v64, v65
	v_mov_b32_e32 v65, v64
	s_nop 1
	v_permlane32_swap_b32_e32 v64, v65
	v_cvt_pk_bf16_f32 v80, v72, v73
	v_cvt_pk_bf16_f32 v81, v66, v67
	v_lshl_add_u64 v[82:83], v[82:83], 0, v[250:251]
	s_nop 1
	v_permlane16_swap_b32_e32 v84, v86
	v_permlane16_swap_b32_e32 v85, v87
	global_store_dwordx4 v[82:83], v[84:87], off
	s_nop 1
	s_nop 1
	v_permlane16_swap_b32_e32 v78, v80
	v_permlane16_swap_b32_e32 v79, v81
	global_store_dwordx4 v[82:83], v[78:81], off offset:256
	s_nop 1
	s_and_saveexec_b64 s[38:39], vcc
	s_cbranch_execz .LBB0_1386
	v_lshlrev_b64 v[66:67], 6, v[184:185]
	v_lshl_add_u64 v[66:67], s[14:15], 0, v[66:67]
	v_lshl_add_u64 v[66:67], s[36:37], 2, v[66:67]
	s_lshl_b32 s10, s53, 2
	v_lshl_add_u64 v[66:67], v[66:67], 0, s[10:11]
	s_waitcnt lgkmcnt(0)
	v_add_f32_e32 v64, v64, v65
	global_store_dword v[66:67], v64, off
.LBB0_1386:
	s_or_b64 exec, exec, s[38:39]
	s_waitcnt vmcnt(16)
	v_permlane16_swap_b32_e32 v180, v182
	v_permlane16_swap_b32_e32 v181, v183
	v_permlane16_swap_b32_e32 v176, v178
	v_permlane16_swap_b32_e32 v177, v179
	v_lshlrev_b64 v[186:187], 11, v[172:173]
	v_lshlrev_b32_e32 v64, 16, v180
	s_waitcnt lgkmcnt(0)
	v_and_b32_e32 v65, 0xffff0000, v180
	v_lshlrev_b32_e32 v66, 16, v181
	v_and_b32_e32 v67, 0xffff0000, v181
	v_pk_add_f32 v[60:61], v[60:61], v[64:65]
	v_pk_add_f32 v[62:63], v[62:63], v[66:67]
	v_cvt_pk_bf16_f32 v68, v60, v61
	v_mul_f32_e32 v61, v61, v61
	v_lshl_add_u64 v[66:67], s[12:13], 0, v[186:187]
	v_fmac_f32_e32 v61, v60, v60
	v_mul_f32_e32 v60, v63, v63
	v_cvt_pk_bf16_f32 v69, v62, v63
	v_lshl_add_u64 v[66:67], v[138:139], 1, v[66:67]
	v_fmac_f32_e32 v60, v62, v62
	v_add_f32_e32 v64, v61, v60
	v_lshlrev_b32_e32 v60, 16, v182
	v_and_b32_e32 v61, 0xffff0000, v182
	v_lshlrev_b32_e32 v62, 16, v183
	v_and_b32_e32 v63, 0xffff0000, v183
	v_pk_add_f32 v[56:57], v[56:57], v[60:61]
	v_pk_add_f32 v[58:59], v[58:59], v[62:63]
	v_cvt_pk_bf16_f32 v70, v56, v57
	v_mul_f32_e32 v57, v57, v57
	v_fmac_f32_e32 v57, v56, v56
	v_mul_f32_e32 v56, v59, v59
	v_fmac_f32_e32 v56, v58, v58
	v_add_f32_e32 v56, v57, v56
	v_add_f32_e32 v61, v64, v56
	v_lshlrev_b32_e32 v56, 16, v176
	v_and_b32_e32 v57, 0xffff0000, v176
	v_lshlrev_b32_e32 v62, 16, v177
	v_and_b32_e32 v63, 0xffff0000, v177
	v_pk_add_f32 v[54:55], v[54:55], v[62:63]
	v_pk_add_f32 v[52:53], v[52:53], v[56:57]
	v_mul_f32_e32 v57, v55, v55
	v_mul_f32_e32 v56, v53, v53
	v_fmac_f32_e32 v56, v52, v52
	v_fmac_f32_e32 v57, v54, v54
	v_add_f32_e32 v56, v56, v57
	v_add_f32_e32 v61, v61, v56
	v_lshlrev_b32_e32 v56, 16, v178
	v_and_b32_e32 v57, 0xffff0000, v178
	v_lshlrev_b32_e32 v62, 16, v179
	v_and_b32_e32 v63, 0xffff0000, v179
	v_pk_add_f32 v[50:51], v[50:51], v[62:63]
	v_pk_add_f32 v[56:57], v[48:49], v[56:57]
	v_mul_f32_e32 v49, v51, v51
	v_mul_f32_e32 v48, v57, v57
	v_fmac_f32_e32 v48, v56, v56
	v_fmac_f32_e32 v49, v50, v50
	v_add_f32_e32 v48, v48, v49
	v_add_f32_e32 v48, v61, v48
	v_mov_b32_e32 v49, v48
	s_nop 1
	v_permlane16_swap_b32_e32 v48, v49
	v_cvt_pk_bf16_f32 v62, v52, v53
	v_cvt_pk_bf16_f32 v63, v54, v55
	v_cvt_pk_bf16_f32 v71, v58, v59
	s_waitcnt lgkmcnt(0)
	v_add_f32_e32 v48, v48, v49
	v_mov_b32_e32 v49, v48
	s_nop 1
	v_permlane32_swap_b32_e32 v48, v49
	v_cvt_pk_bf16_f32 v64, v56, v57
	v_cvt_pk_bf16_f32 v65, v50, v51
	v_lshl_add_u64 v[66:67], v[66:67], 0, v[250:251]
	s_nop 1
	v_permlane16_swap_b32_e32 v68, v70
	v_permlane16_swap_b32_e32 v69, v71
	global_store_dwordx4 v[66:67], v[68:71], off
	s_nop 1
	s_nop 1
	v_permlane16_swap_b32_e32 v62, v64
	v_permlane16_swap_b32_e32 v63, v65
	global_store_dwordx4 v[66:67], v[62:65], off offset:256
	s_nop 1
	s_and_saveexec_b64 s[38:39], vcc
	s_cbranch_execz .LBB0_1388
	v_lshlrev_b64 v[50:51], 6, v[172:173]
	v_lshl_add_u64 v[50:51], s[14:15], 0, v[50:51]
	v_lshl_add_u64 v[50:51], s[36:37], 2, v[50:51]
	s_lshl_b32 s10, s53, 2
	v_lshl_add_u64 v[50:51], v[50:51], 0, s[10:11]
	s_waitcnt lgkmcnt(0)
	v_add_f32_e32 v48, v48, v49
	global_store_dword v[50:51], v48, off
; #define PG8_GAS __attribute__((address_space(1)))
; __device__ __forceinline__ unsigned pk2_(float lo, float hi) { f32x2c_t v = {lo, hi}; bf16x2c_t b = __builtin_convertvector(v, bf16x2c_t); return __builtin_bit_cast(unsigned, b); }
;     __device__ __forceinline__ void operator()(const f32x4 (&acc)[2][2][4][2], const Unit& u, int wr, int wc, int fr, int fq) const {
;     ...
;         for (int ai = 0; ai < 2; ++ai)
; #pragma unroll
;             for (int m = 0; m < 4; ++m) {
;                 const int r = row0 + ai * HALF + m * 16; const size_t off = (size_t)r * 1024 + col0; float ss = 0.f;
; #pragma unroll
;                 for (int bj = 0; bj < 2; ++bj)
; #pragma unroll
;                     for (int n = 0; n < 2; ++n) {
;                         const u32x2v w0 = bsv[ai][m][bj][n]; f32x4 bs;
;                         bs[0] = __builtin_bit_cast(float, w0.x << 16); bs[1] = __builtin_bit_cast(float, w0.x & 0xffff0000u); bs[2] = __builtin_bit_cast(float, w0.y << 16); bs[3] = __builtin_bit_cast(float, w0.y & 0xffff0000u);
;                         const f32x4 v = bs + acc[ai][bj][m][n] * alpha;
;                         { u32x2v w; w.x = pk2_(v[0], v[1]); w.y = pk2_(v[2], v[3]); *(PG8_GAS u32x2v*)(hb + off + bj * HALF + n * 16) = w; }
;                         ss += (v[0] * v[0] + v[1] * v[1]) + (v[2] * v[2] + v[3] * v[3]);
;                     }
;                 ss += __shfl_xor(ss, 16); ss += __shfl_xor(ss, 32);
;                 if (fq == 0) ((PG8_GAS float*)parts)[(size_t)r * 16 + u.pn * 4 + wc] = ss;
;             }
.LBB0_1388:
	s_or_b64 exec, exec, s[38:39]
	s_waitcnt vmcnt(16)
	v_permlane16_swap_b32_e32 v168, v170
	v_permlane16_swap_b32_e32 v169, v171
	v_permlane16_swap_b32_e32 v164, v166
	v_permlane16_swap_b32_e32 v165, v167
	v_lshlrev_b64 v[174:175], 11, v[160:161]
	v_lshlrev_b32_e32 v48, 16, v168
	s_waitcnt lgkmcnt(0)
	v_and_b32_e32 v49, 0xffff0000, v168
	v_lshlrev_b32_e32 v50, 16, v169
	v_and_b32_e32 v51, 0xffff0000, v169
	v_pk_add_f32 v[44:45], v[44:45], v[48:49]
	v_pk_add_f32 v[46:47], v[46:47], v[50:51]
	v_cvt_pk_bf16_f32 v52, v44, v45
	v_mul_f32_e32 v45, v45, v45
	v_lshl_add_u64 v[50:51], s[12:13], 0, v[174:175]
	v_fmac_f32_e32 v45, v44, v44
	v_mul_f32_e32 v44, v47, v47
	v_cvt_pk_bf16_f32 v53, v46, v47
	v_lshl_add_u64 v[50:51], v[138:139], 1, v[50:51]
	v_fmac_f32_e32 v44, v46, v46
	v_add_f32_e32 v48, v45, v44
	v_lshlrev_b32_e32 v44, 16, v170
	v_and_b32_e32 v45, 0xffff0000, v170
	v_lshlrev_b32_e32 v46, 16, v171
	v_and_b32_e32 v47, 0xffff0000, v171
	v_pk_add_f32 v[40:41], v[40:41], v[44:45]
	v_pk_add_f32 v[42:43], v[42:43], v[46:47]
	v_cvt_pk_bf16_f32 v54, v40, v41
	v_mul_f32_e32 v41, v41, v41
	v_fmac_f32_e32 v41, v40, v40
	v_mul_f32_e32 v40, v43, v43
	v_fmac_f32_e32 v40, v42, v42
	v_add_f32_e32 v40, v41, v40
	v_add_f32_e32 v45, v48, v40
	v_lshlrev_b32_e32 v40, 16, v164
	v_and_b32_e32 v41, 0xffff0000, v164
	v_lshlrev_b32_e32 v46, 16, v165
	v_and_b32_e32 v47, 0xffff0000, v165
	v_pk_add_f32 v[38:39], v[38:39], v[46:47]
	v_pk_add_f32 v[36:37], v[36:37], v[40:41]
	v_mul_f32_e32 v41, v39, v39
	v_mul_f32_e32 v40, v37, v37
	v_fmac_f32_e32 v40, v36, v36
	v_fmac_f32_e32 v41, v38, v38
	v_add_f32_e32 v40, v40, v41
	v_add_f32_e32 v45, v45, v40
	v_lshlrev_b32_e32 v40, 16, v166
	v_and_b32_e32 v41, 0xffff0000, v166
	v_lshlrev_b32_e32 v46, 16, v167
	v_and_b32_e32 v47, 0xffff0000, v167
	v_pk_add_f32 v[34:35], v[34:35], v[46:47]
	v_pk_add_f32 v[40:41], v[32:33], v[40:41]
	v_mul_f32_e32 v33, v35, v35
	v_mul_f32_e32 v32, v41, v41
	v_fmac_f32_e32 v32, v40, v40
	v_fmac_f32_e32 v33, v34, v34
	v_add_f32_e32 v32, v32, v33
	v_add_f32_e32 v32, v45, v32
	v_mov_b32_e32 v33, v32
	s_nop 1
	v_permlane16_swap_b32_e32 v32, v33
	v_cvt_pk_bf16_f32 v46, v36, v37
	v_cvt_pk_bf16_f32 v47, v38, v39
	v_cvt_pk_bf16_f32 v55, v42, v43
	s_waitcnt lgkmcnt(0)
	v_add_f32_e32 v32, v32, v33
	v_mov_b32_e32 v33, v32
	s_nop 1
	v_permlane32_swap_b32_e32 v32, v33
	v_cvt_pk_bf16_f32 v48, v40, v41
	v_cvt_pk_bf16_f32 v49, v34, v35
	v_lshl_add_u64 v[50:51], v[50:51], 0, v[250:251]
	s_nop 1
	v_permlane16_swap_b32_e32 v52, v54
	v_permlane16_swap_b32_e32 v53, v55
	global_store_dwordx4 v[50:51], v[52:55], off
	s_nop 1
	s_nop 1
	v_permlane16_swap_b32_e32 v46, v48
	v_permlane16_swap_b32_e32 v47, v49
	global_store_dwordx4 v[50:51], v[46:49], off offset:256
	s_nop 1
	s_and_saveexec_b64 s[38:39], vcc
	s_cbranch_execz .LBB0_1390
	v_lshlrev_b64 v[34:35], 6, v[160:161]
	v_lshl_add_u64 v[34:35], s[14:15], 0, v[34:35]
	v_lshl_add_u64 v[34:35], s[36:37], 2, v[34:35]
	s_lshl_b32 s10, s53, 2
	v_lshl_add_u64 v[34:35], v[34:35], 0, s[10:11]
	s_waitcnt lgkmcnt(0)
	v_add_f32_e32 v32, v32, v33
	global_store_dword v[34:35], v32, off
; #define PG8_GAS __attribute__((address_space(1)))
; __device__ __forceinline__ unsigned pk2_(float lo, float hi) { f32x2c_t v = {lo, hi}; bf16x2c_t b = __builtin_convertvector(v, bf16x2c_t); return __builtin_bit_cast(unsigned, b); }
;     __device__ __forceinline__ void operator()(const f32x4 (&acc)[2][2][4][2], const Unit& u, int wr, int wc, int fr, int fq) const {
;     ...
;         for (int ai = 0; ai < 2; ++ai)
; #pragma unroll
;             for (int m = 0; m < 4; ++m) {
;                 const int r = row0 + ai * HALF + m * 16; const size_t off = (size_t)r * 1024 + col0; float ss = 0.f;
; #pragma unroll
;                 for (int bj = 0; bj < 2; ++bj)
; #pragma unroll
;                     for (int n = 0; n < 2; ++n) {
;                         const u32x2v w0 = bsv[ai][m][bj][n]; f32x4 bs;
;                         bs[0] = __builtin_bit_cast(float, w0.x << 16); bs[1] = __builtin_bit_cast(float, w0.x & 0xffff0000u); bs[2] = __builtin_bit_cast(float, w0.y << 16); bs[3] = __builtin_bit_cast(float, w0.y & 0xffff0000u);
;                         const f32x4 v = bs + acc[ai][bj][m][n] * alpha;
;                         { u32x2v w; w.x = pk2_(v[0], v[1]); w.y = pk2_(v[2], v[3]); *(PG8_GAS u32x2v*)(hb + off + bj * HALF + n * 16) = w; }
;                         ss += (v[0] * v[0] + v[1] * v[1]) + (v[2] * v[2] + v[3] * v[3]);
;                     }
;                 ss += __shfl_xor(ss, 16); ss += __shfl_xor(ss, 32);
;                 if (fq == 0) ((PG8_GAS float*)parts)[(size_t)r * 16 + u.pn * 4 + wc] = ss;
;             }
.LBB0_1390:
	s_or_b64 exec, exec, s[38:39]
	s_waitcnt vmcnt(16)
	v_permlane16_swap_b32_e32 v156, v158
	v_permlane16_swap_b32_e32 v157, v159
	v_permlane16_swap_b32_e32 v152, v154
	v_permlane16_swap_b32_e32 v153, v155
	v_lshlrev_b64 v[162:163], 11, v[148:149]
	v_lshlrev_b32_e32 v32, 16, v156
	s_waitcnt lgkmcnt(0)
	v_and_b32_e32 v33, 0xffff0000, v156
	v_lshlrev_b32_e32 v34, 16, v157
	v_and_b32_e32 v35, 0xffff0000, v157
	v_pk_add_f32 v[28:29], v[28:29], v[32:33]
	v_pk_add_f32 v[30:31], v[30:31], v[34:35]
	v_cvt_pk_bf16_f32 v36, v28, v29
	v_mul_f32_e32 v29, v29, v29
	v_lshl_add_u64 v[34:35], s[12:13], 0, v[162:163]
	v_fmac_f32_e32 v29, v28, v28
	v_mul_f32_e32 v28, v31, v31
	v_cvt_pk_bf16_f32 v37, v30, v31
	v_lshl_add_u64 v[34:35], v[138:139], 1, v[34:35]
	v_fmac_f32_e32 v28, v30, v30
	v_add_f32_e32 v32, v29, v28
	v_lshlrev_b32_e32 v28, 16, v158
	v_and_b32_e32 v29, 0xffff0000, v158
	v_lshlrev_b32_e32 v30, 16, v159
	v_and_b32_e32 v31, 0xffff0000, v159
	v_pk_add_f32 v[24:25], v[24:25], v[28:29]
	v_pk_add_f32 v[26:27], v[26:27], v[30:31]
	v_cvt_pk_bf16_f32 v38, v24, v25
	v_mul_f32_e32 v25, v25, v25
	v_fmac_f32_e32 v25, v24, v24
	v_mul_f32_e32 v24, v27, v27
	v_fmac_f32_e32 v24, v26, v26
	v_add_f32_e32 v24, v25, v24
	v_add_f32_e32 v29, v32, v24
	v_lshlrev_b32_e32 v24, 16, v152
	v_and_b32_e32 v25, 0xffff0000, v152
	v_lshlrev_b32_e32 v30, 16, v153
	v_and_b32_e32 v31, 0xffff0000, v153
	v_pk_add_f32 v[22:23], v[22:23], v[30:31]
	v_pk_add_f32 v[20:21], v[20:21], v[24:25]
	v_mul_f32_e32 v25, v23, v23
	v_mul_f32_e32 v24, v21, v21
	v_fmac_f32_e32 v24, v20, v20
	v_fmac_f32_e32 v25, v22, v22
	v_add_f32_e32 v24, v24, v25
	v_add_f32_e32 v29, v29, v24
	v_lshlrev_b32_e32 v24, 16, v154
	v_and_b32_e32 v25, 0xffff0000, v154
	v_lshlrev_b32_e32 v30, 16, v155
	v_and_b32_e32 v31, 0xffff0000, v155
	v_pk_add_f32 v[18:19], v[18:19], v[30:31]
	v_pk_add_f32 v[24:25], v[16:17], v[24:25]
	v_mul_f32_e32 v17, v19, v19
	v_mul_f32_e32 v16, v25, v25
	v_fmac_f32_e32 v16, v24, v24
	v_fmac_f32_e32 v17, v18, v18
	v_add_f32_e32 v16, v16, v17
	v_add_f32_e32 v16, v29, v16
	v_mov_b32_e32 v17, v16
	s_nop 1
	v_permlane16_swap_b32_e32 v16, v17
	v_cvt_pk_bf16_f32 v30, v20, v21
	v_cvt_pk_bf16_f32 v31, v22, v23
	v_cvt_pk_bf16_f32 v39, v26, v27
	s_waitcnt lgkmcnt(0)
	v_add_f32_e32 v16, v16, v17
	v_mov_b32_e32 v17, v16
	s_nop 1
	v_permlane32_swap_b32_e32 v16, v17
	v_cvt_pk_bf16_f32 v32, v24, v25
	v_cvt_pk_bf16_f32 v33, v18, v19
	v_lshl_add_u64 v[34:35], v[34:35], 0, v[250:251]
	s_nop 1
	v_permlane16_swap_b32_e32 v36, v38
	v_permlane16_swap_b32_e32 v37, v39
	global_store_dwordx4 v[34:35], v[36:39], off
	s_nop 1
	s_nop 1
	v_permlane16_swap_b32_e32 v30, v32
	v_permlane16_swap_b32_e32 v31, v33
	global_store_dwordx4 v[34:35], v[30:33], off offset:256
	s_nop 1
	s_and_saveexec_b64 s[38:39], vcc
	s_cbranch_execz .LBB0_1392
	v_lshlrev_b64 v[18:19], 6, v[148:149]
	v_lshl_add_u64 v[18:19], s[14:15], 0, v[18:19]
	v_lshl_add_u64 v[18:19], s[36:37], 2, v[18:19]
	s_lshl_b32 s10, s53, 2
	v_lshl_add_u64 v[18:19], v[18:19], 0, s[10:11]
	s_waitcnt lgkmcnt(0)
	v_add_f32_e32 v16, v16, v17
	global_store_dword v[18:19], v16, off
.LBB0_1392:
	s_or_b64 exec, exec, s[38:39]
	s_waitcnt vmcnt(16)
	v_permlane16_swap_b32_e32 v144, v146
	v_permlane16_swap_b32_e32 v145, v147
	v_permlane16_swap_b32_e32 v140, v142
	v_permlane16_swap_b32_e32 v141, v143
	v_lshlrev_b64 v[150:151], 11, v[136:137]
	v_lshlrev_b32_e32 v16, 16, v144
	s_waitcnt lgkmcnt(0)
	v_and_b32_e32 v17, 0xffff0000, v144
	v_lshlrev_b32_e32 v18, 16, v145
	v_and_b32_e32 v19, 0xffff0000, v145
	v_pk_add_f32 v[12:13], v[12:13], v[16:17]
	v_pk_add_f32 v[14:15], v[14:15], v[18:19]
	v_cvt_pk_bf16_f32 v20, v12, v13
	v_mul_f32_e32 v13, v13, v13
	v_lshl_add_u64 v[18:19], s[12:13], 0, v[150:151]
	v_fmac_f32_e32 v13, v12, v12
	v_mul_f32_e32 v12, v15, v15
	v_cvt_pk_bf16_f32 v21, v14, v15
	v_lshl_add_u64 v[18:19], v[138:139], 1, v[18:19]
	v_fmac_f32_e32 v12, v14, v14
	v_add_f32_e32 v16, v13, v12
	v_lshlrev_b32_e32 v12, 16, v146
	v_and_b32_e32 v13, 0xffff0000, v146
	v_lshlrev_b32_e32 v14, 16, v147
	v_and_b32_e32 v15, 0xffff0000, v147
	v_pk_add_f32 v[8:9], v[8:9], v[12:13]
	v_pk_add_f32 v[10:11], v[10:11], v[14:15]
	v_cvt_pk_bf16_f32 v22, v8, v9
	v_mul_f32_e32 v9, v9, v9
	v_fmac_f32_e32 v9, v8, v8
	v_mul_f32_e32 v8, v11, v11
	v_fmac_f32_e32 v8, v10, v10
	v_add_f32_e32 v8, v9, v8
	v_add_f32_e32 v13, v16, v8
	v_lshlrev_b32_e32 v8, 16, v140
	v_and_b32_e32 v9, 0xffff0000, v140
	v_lshlrev_b32_e32 v14, 16, v141
	v_and_b32_e32 v15, 0xffff0000, v141
	v_pk_add_f32 v[6:7], v[6:7], v[14:15]
	v_pk_add_f32 v[4:5], v[4:5], v[8:9]
	v_mul_f32_e32 v9, v7, v7
	v_mul_f32_e32 v8, v5, v5
	v_fmac_f32_e32 v8, v4, v4
	v_fmac_f32_e32 v9, v6, v6
	v_add_f32_e32 v8, v8, v9
	v_add_f32_e32 v13, v13, v8
	v_lshlrev_b32_e32 v8, 16, v142
	v_and_b32_e32 v9, 0xffff0000, v142
	v_lshlrev_b32_e32 v14, 16, v143
	v_and_b32_e32 v15, 0xffff0000, v143
	v_pk_add_f32 v[2:3], v[2:3], v[14:15]
	v_pk_add_f32 v[8:9], v[0:1], v[8:9]
	v_mul_f32_e32 v1, v3, v3
	v_mul_f32_e32 v0, v9, v9
	v_fmac_f32_e32 v0, v8, v8
	v_fmac_f32_e32 v1, v2, v2
	v_add_f32_e32 v0, v0, v1
	v_add_f32_e32 v0, v13, v0
	v_mov_b32_e32 v1, v0
	s_nop 1
	v_permlane16_swap_b32_e32 v0, v1
	v_cvt_pk_bf16_f32 v14, v4, v5
	v_cvt_pk_bf16_f32 v15, v6, v7
	v_cvt_pk_bf16_f32 v23, v10, v11
	s_waitcnt lgkmcnt(0)
	v_add_f32_e32 v0, v0, v1
	v_mov_b32_e32 v1, v0
	s_nop 1
	v_permlane32_swap_b32_e32 v0, v1
	v_cvt_pk_bf16_f32 v16, v8, v9
	v_cvt_pk_bf16_f32 v17, v2, v3
	v_lshl_add_u64 v[18:19], v[18:19], 0, v[250:251]
	s_nop 1
	v_permlane16_swap_b32_e32 v20, v22
	v_permlane16_swap_b32_e32 v21, v23
	global_store_dwordx4 v[18:19], v[20:23], off
	s_nop 1
	s_nop 1
	v_permlane16_swap_b32_e32 v14, v16
	v_permlane16_swap_b32_e32 v15, v17
	global_store_dwordx4 v[18:19], v[14:17], off offset:256
	s_nop 1
	s_and_saveexec_b64 s[38:39], vcc
	s_cbranch_execz .LBB0_1394
	v_lshlrev_b64 v[2:3], 6, v[136:137]
	v_lshl_add_u64 v[2:3], s[14:15], 0, v[2:3]
	v_lshl_add_u64 v[2:3], s[36:37], 2, v[2:3]
	s_lshl_b32 s10, s53, 2
	v_lshl_add_u64 v[2:3], v[2:3], 0, s[10:11]
	s_waitcnt lgkmcnt(0)
	v_add_f32_e32 v0, v0, v1
	global_store_dword v[2:3], v0, off

; #define PG8_GAS __attribute__((address_space(1)))
; __device__ __forceinline__ unsigned pk2_(float lo, float hi) { f32x2c_t v = {lo, hi}; bf16x2c_t b = __builtin_convertvector(v, bf16x2c_t); return __builtin_bit_cast(unsigned, b); }
;     __device__ __forceinline__ void operator()(const f32x4 (&acc)[2][2][4][2], const Unit& u, int wr, int wc, int fr, int fq) const {
;     ...
;         const int row0 = u.pm * BM + wr * 64 + fr, col0 = u.pn * BM + wc * 32 + 4 * fq;
;         u32x2v bsv[2][4][2][2];
; #pragma unroll
;         for (int ai = 0; ai < 2; ++ai)
; #pragma unroll
;             for (int m = 0; m < 4; ++m) { const size_t off = (size_t)(row0 + ai * HALF + m * 16) * 1024 + col0;
; #pragma unroll
;                 for (int bj = 0; bj < 2; ++bj)
; #pragma unroll
;                     for (int n = 0; n < 2; ++n) bsv[ai][m][bj][n] = *(const PG8_GAS u32x2v*)(hbase + off + bj * HALF + n * 16); }
; #pragma unroll
;         for (int ai = 0; ai < 2; ++ai)
; #pragma unroll
;             for (int m = 0; m < 4; ++m) {
;                 const int r = row0 + ai * HALF + m * 16; const size_t off = (size_t)r * 1024 + col0; float ss = 0.f;
; #pragma unroll
;                 for (int bj = 0; bj < 2; ++bj)
; #pragma unroll
;                     for (int n = 0; n < 2; ++n) {
;                         const u32x2v w0 = bsv[ai][m][bj][n]; f32x4 bs;
;                         bs[0] = __builtin_bit_cast(float, w0.x << 16); bs[1] = __builtin_bit_cast(float, w0.x & 0xffff0000u); bs[2] = __builtin_bit_cast(float, w0.y << 16); bs[3] = __builtin_bit_cast(float, w0.y & 0xffff0000u);
;                         const f32x4 v = bs + acc[ai][bj][m][n] * alpha;
;                         { u32x2v w; w.x = pk2_(v[0], v[1]); w.y = pk2_(v[2], v[3]); *(PG8_GAS u32x2v*)(hb + off + bj * HALF + n * 16) = w; }
;                         ss += (v[0] * v[0] + v[1] * v[1]) + (v[2] * v[2] + v[3] * v[3]);
;                     }
;                 ss += __shfl_xor(ss, 16); ss += __shfl_xor(ss, 32);
;                 if (fq == 0) ((PG8_GAS float*)parts)[(size_t)r * 16 + u.pn * 4 + wc] = ss;
;             }
.LBB0_1735:
	s_lshl_b32 s30, s57, 8
	v_mov_b32_e32 v136, v252
	s_add_i32 s30, s30, s48
	v_cmp_lt_i32_e32 vcc, v227, v226
	v_and_or_b32 v220, v136, 15, s30
	s_lshl_b32 s30, s12, 8
	v_bfe_u32 v244, v136, 4, 2
	s_or_b32 s30, s30, s49
	v_lshl_or_b32 v138, v244, 2, s30
	v_ashrrev_i32_e32 v139, 31, v138
	v_lshlrev_b64 v[224:225], 1, v[138:139]
	v_ashrrev_i32_e32 v221, 31, v220
	v_lshl_add_u64 v[140:141], s[14:15], 0, v[224:225]
	v_lshlrev_b64 v[234:235], 11, v[220:221]
	v_lshl_add_u64 v[136:137], v[140:141], 0, v[234:235]
	v_bfe_u32 v250, v252, 4, 1
	v_mul_u32_u24_e32 v250, 24, v250
	v_mov_b32_e32 v251, 0
	v_lshl_add_u64 v[136:137], v[136:137], 0, v[250:251]
	global_load_dwordx4 v[236:239], v[136:137], off
	global_load_dwordx4 v[240:243], v[136:137], off offset:256
	v_or_b32_e32 v208, 16, v220
	v_ashrrev_i32_e32 v209, 31, v208
	v_or_b32_e32 v196, 32, v220
	v_lshlrev_b64 v[218:219], 11, v[208:209]
	v_ashrrev_i32_e32 v197, 31, v196
	v_or_b32_e32 v184, 48, v220
	v_lshl_add_u64 v[136:137], v[140:141], 0, v[218:219]
	v_lshlrev_b64 v[206:207], 11, v[196:197]
	v_ashrrev_i32_e32 v185, 31, v184
	v_add_u32_e32 v172, 0x80, v220
	v_lshl_add_u64 v[136:137], v[136:137], 0, v[250:251]
	global_load_dwordx4 v[216:219], v[136:137], off
	global_load_dwordx4 v[212:215], v[136:137], off offset:256
	v_lshl_add_u64 v[136:137], v[140:141], 0, v[206:207]
	v_lshlrev_b64 v[194:195], 11, v[184:185]
	v_ashrrev_i32_e32 v173, 31, v172
	v_add_u32_e32 v160, 0x90, v220
	v_lshl_add_u64 v[136:137], v[136:137], 0, v[250:251]
	global_load_dwordx4 v[204:207], v[136:137], off
	global_load_dwordx4 v[200:203], v[136:137], off offset:256
	v_lshl_add_u64 v[136:137], v[140:141], 0, v[194:195]
	v_lshlrev_b64 v[182:183], 11, v[172:173]
	v_ashrrev_i32_e32 v161, 31, v160
	v_add_u32_e32 v148, 0xa0, v220
	v_lshl_add_u64 v[136:137], v[136:137], 0, v[250:251]
	global_load_dwordx4 v[192:195], v[136:137], off
	global_load_dwordx4 v[188:191], v[136:137], off offset:256
	v_lshl_add_u64 v[136:137], v[140:141], 0, v[182:183]
	v_lshlrev_b64 v[170:171], 11, v[160:161]
	v_ashrrev_i32_e32 v149, 31, v148
	v_lshl_add_u64 v[136:137], v[136:137], 0, v[250:251]
	global_load_dwordx4 v[180:183], v[136:137], off
	global_load_dwordx4 v[176:179], v[136:137], off offset:256
	v_lshl_add_u64 v[136:137], v[140:141], 0, v[170:171]
	v_lshlrev_b64 v[158:159], 11, v[148:149]
	v_lshl_add_u64 v[136:137], v[136:137], 0, v[250:251]
	global_load_dwordx4 v[168:171], v[136:137], off
	global_load_dwordx4 v[164:167], v[136:137], off offset:256
	v_lshl_add_u64 v[136:137], v[140:141], 0, v[158:159]
	v_lshl_add_u64 v[136:137], v[136:137], 0, v[250:251]
	global_load_dwordx4 v[156:159], v[136:137], off
	global_load_dwordx4 v[152:155], v[136:137], off offset:256
	v_add_u32_e32 v136, 0xb0, v220
	v_ashrrev_i32_e32 v137, 31, v136
	v_lshlrev_b64 v[146:147], 11, v[136:137]
	v_lshl_add_u64 v[140:141], v[140:141], 0, v[146:147]
	v_lshl_add_u64 v[140:141], v[140:141], 0, v[250:251]
	global_load_dwordx4 v[144:147], v[140:141], off
	global_load_dwordx4 v[140:143], v[140:141], off offset:256
	s_nop 0
	v_xor_b32_e32 v245, 32, v253
	v_cndmask_b32_e32 v232, v253, v227, vcc
	v_cmp_lt_i32_e32 vcc, v245, v226
	v_lshlrev_b32_e32 v233, 2, v232
	v_lshl_add_u64 v[234:235], s[14:15], 0, v[234:235]
	v_cndmask_b32_e32 v232, v253, v245, vcc
	v_cmp_eq_u32_e32 vcc, 0, v244
	v_lshl_add_u64 v[224:225], v[234:235], 0, v[224:225]
	v_lshlrev_b32_e32 v232, 2, v232
	s_lshl_b32 s30, s12, 2
	s_ashr_i32 s31, s30, 31
	s_waitcnt vmcnt(14)
	v_permlane16_swap_b32_e32 v236, v238
	v_permlane16_swap_b32_e32 v237, v239
	v_permlane16_swap_b32_e32 v240, v242
	v_permlane16_swap_b32_e32 v241, v243
	v_lshlrev_b32_e32 v244, 16, v236
	v_and_b32_e32 v245, 0xffff0000, v236
	v_lshlrev_b32_e32 v236, 16, v237
	v_and_b32_e32 v237, 0xffff0000, v237
	v_pk_fma_f32 v[124:125], v[124:125], 0.5, v[244:245] op_sel_hi:[1,0,1]
	v_pk_fma_f32 v[126:127], v[126:127], 0.5, v[236:237] op_sel_hi:[1,0,1]
	v_cvt_pk_bf16_f32 v236, v124, v125
	v_mul_f32_e32 v125, v125, v125
	v_fmac_f32_e32 v125, v124, v124
	v_mul_f32_e32 v124, v127, v127
	v_fmac_f32_e32 v124, v126, v126
	v_add_f32_e32 v234, v125, v124
	v_lshlrev_b32_e32 v124, 16, v238
	v_and_b32_e32 v125, 0xffff0000, v238
	v_cvt_pk_bf16_f32 v237, v126, v127
	v_lshlrev_b32_e32 v126, 16, v239
	v_and_b32_e32 v127, 0xffff0000, v239
	v_pk_fma_f32 v[120:121], v[120:121], 0.5, v[124:125] op_sel_hi:[1,0,1]
	v_pk_fma_f32 v[122:123], v[122:123], 0.5, v[126:127] op_sel_hi:[1,0,1]
	v_cvt_pk_bf16_f32 v124, v120, v121
	v_mul_f32_e32 v121, v121, v121
	v_fmac_f32_e32 v121, v120, v120
	v_mul_f32_e32 v120, v123, v123
	v_fmac_f32_e32 v120, v122, v122
	v_add_f32_e32 v120, v121, v120
	v_add_f32_e32 v125, v234, v120
	v_lshlrev_b32_e32 v120, 16, v240
	v_and_b32_e32 v121, 0xffff0000, v240
	v_lshlrev_b32_e32 v126, 16, v241
	v_and_b32_e32 v127, 0xffff0000, v241
	v_pk_fma_f32 v[118:119], v[118:119], 0.5, v[126:127] op_sel_hi:[1,0,1]
	v_pk_fma_f32 v[116:117], v[116:117], 0.5, v[120:121] op_sel_hi:[1,0,1]
	v_mul_f32_e32 v121, v119, v119
	v_mul_f32_e32 v120, v117, v117
	v_fmac_f32_e32 v120, v116, v116
	v_fmac_f32_e32 v121, v118, v118
	v_add_f32_e32 v120, v120, v121
	v_add_f32_e32 v125, v125, v120
	v_lshlrev_b32_e32 v120, 16, v242
	v_and_b32_e32 v121, 0xffff0000, v242
	v_lshlrev_b32_e32 v126, 16, v243
	v_and_b32_e32 v127, 0xffff0000, v243
	v_pk_fma_f32 v[114:115], v[114:115], 0.5, v[126:127] op_sel_hi:[1,0,1]
	v_pk_fma_f32 v[120:121], v[112:113], 0.5, v[120:121] op_sel_hi:[1,0,1]
	v_mul_f32_e32 v113, v115, v115
	v_mul_f32_e32 v112, v121, v121
	v_fmac_f32_e32 v112, v120, v120
	v_fmac_f32_e32 v113, v114, v114
	v_add_f32_e32 v112, v112, v113
	v_add_f32_e32 v112, v125, v112
	v_mov_b32_e32 v113, v112
	s_nop 1
	v_permlane16_swap_b32_e32 v112, v113
	v_cvt_pk_bf16_f32 v116, v116, v117
	v_cvt_pk_bf16_f32 v117, v118, v119
	v_cvt_pk_bf16_f32 v125, v122, v123
	global_store_dwordx2 v[224:225], v[116:117], off offset:256
	s_waitcnt lgkmcnt(0)
	v_add_f32_e32 v112, v112, v113
	v_mov_b32_e32 v113, v112
	s_nop 1
	v_permlane32_swap_b32_e32 v112, v113
	v_cvt_pk_bf16_f32 v116, v120, v121
	v_cvt_pk_bf16_f32 v117, v114, v115
	global_store_dwordx2 v[224:225], v[236:237], off
	global_store_dwordx2 v[224:225], v[124:125], off offset:32
	global_store_dwordx2 v[224:225], v[116:117], off offset:288
	s_and_saveexec_b64 s[34:35], vcc
	s_cbranch_execz .LBB0_1737
	v_lshlrev_b64 v[114:115], 6, v[220:221]
	v_lshl_add_u64 v[114:115], s[16:17], 0, v[114:115]
	v_lshl_add_u64 v[114:115], s[30:31], 2, v[114:115]
	s_lshl_b32 s12, s47, 2
	v_lshl_add_u64 v[114:115], v[114:115], 0, s[12:13]
	s_waitcnt lgkmcnt(0)
	v_add_f32_e32 v112, v112, v113
	global_store_dword v[114:115], v112, off
; #define PG8_GAS __attribute__((address_space(1)))
; __device__ __forceinline__ unsigned pk2_(float lo, float hi) { f32x2c_t v = {lo, hi}; bf16x2c_t b = __builtin_convertvector(v, bf16x2c_t); return __builtin_bit_cast(unsigned, b); }
;     __device__ __forceinline__ void operator()(const f32x4 (&acc)[2][2][4][2], const Unit& u, int wr, int wc, int fr, int fq) const {
;     ...
;         for (int ai = 0; ai < 2; ++ai)
; #pragma unroll
;             for (int m = 0; m < 4; ++m) {
;                 const int r = row0 + ai * HALF + m * 16; const size_t off = (size_t)r * 1024 + col0; float ss = 0.f;
; #pragma unroll
;                 for (int bj = 0; bj < 2; ++bj)
; #pragma unroll
;                     for (int n = 0; n < 2; ++n) {
;                         const u32x2v w0 = bsv[ai][m][bj][n]; f32x4 bs;
;                         bs[0] = __builtin_bit_cast(float, w0.x << 16); bs[1] = __builtin_bit_cast(float, w0.x & 0xffff0000u); bs[2] = __builtin_bit_cast(float, w0.y << 16); bs[3] = __builtin_bit_cast(float, w0.y & 0xffff0000u);
;                         const f32x4 v = bs + acc[ai][bj][m][n] * alpha;
;                         { u32x2v w; w.x = pk2_(v[0], v[1]); w.y = pk2_(v[2], v[3]); *(PG8_GAS u32x2v*)(hb + off + bj * HALF + n * 16) = w; }
;                         ss += (v[0] * v[0] + v[1] * v[1]) + (v[2] * v[2] + v[3] * v[3]);
;                     }
;                 ss += __shfl_xor(ss, 16); ss += __shfl_xor(ss, 32);
;                 if (fq == 0) ((PG8_GAS float*)parts)[(size_t)r * 16 + u.pn * 4 + wc] = ss;
;             }
.LBB0_1737:
	s_or_b64 exec, exec, s[34:35]
	s_waitcnt vmcnt(16)
	v_permlane16_swap_b32_e32 v216, v218
	v_permlane16_swap_b32_e32 v217, v219
	v_permlane16_swap_b32_e32 v212, v214
	v_permlane16_swap_b32_e32 v213, v215
	v_lshlrev_b64 v[222:223], 11, v[208:209]
	v_lshlrev_b32_e32 v112, 16, v216
	s_waitcnt lgkmcnt(0)
	v_and_b32_e32 v113, 0xffff0000, v216
	v_lshlrev_b32_e32 v114, 16, v217
	v_and_b32_e32 v115, 0xffff0000, v217
	v_pk_fma_f32 v[108:109], v[108:109], 0.5, v[112:113] op_sel_hi:[1,0,1]
	v_pk_fma_f32 v[110:111], v[110:111], 0.5, v[114:115] op_sel_hi:[1,0,1]
	v_cvt_pk_bf16_f32 v116, v108, v109
	v_mul_f32_e32 v109, v109, v109
	v_lshl_add_u64 v[114:115], s[14:15], 0, v[222:223]
	v_fmac_f32_e32 v109, v108, v108
	v_mul_f32_e32 v108, v111, v111
	v_cvt_pk_bf16_f32 v117, v110, v111
	v_lshl_add_u64 v[114:115], v[138:139], 1, v[114:115]
	v_fmac_f32_e32 v108, v110, v110
	v_add_f32_e32 v112, v109, v108
	v_lshlrev_b32_e32 v108, 16, v218
	v_and_b32_e32 v109, 0xffff0000, v218
	v_lshlrev_b32_e32 v110, 16, v219
	v_and_b32_e32 v111, 0xffff0000, v219
	v_pk_fma_f32 v[104:105], v[104:105], 0.5, v[108:109] op_sel_hi:[1,0,1]
	v_pk_fma_f32 v[106:107], v[106:107], 0.5, v[110:111] op_sel_hi:[1,0,1]
	v_cvt_pk_bf16_f32 v118, v104, v105
	v_mul_f32_e32 v105, v105, v105
	v_fmac_f32_e32 v105, v104, v104
	v_mul_f32_e32 v104, v107, v107
	v_fmac_f32_e32 v104, v106, v106
	v_add_f32_e32 v104, v105, v104
	v_add_f32_e32 v109, v112, v104
	v_lshlrev_b32_e32 v104, 16, v212
	v_and_b32_e32 v105, 0xffff0000, v212
	v_lshlrev_b32_e32 v110, 16, v213
	v_and_b32_e32 v111, 0xffff0000, v213
	v_pk_fma_f32 v[102:103], v[102:103], 0.5, v[110:111] op_sel_hi:[1,0,1]
	v_pk_fma_f32 v[100:101], v[100:101], 0.5, v[104:105] op_sel_hi:[1,0,1]
	v_mul_f32_e32 v105, v103, v103
	v_mul_f32_e32 v104, v101, v101
	v_fmac_f32_e32 v104, v100, v100
	v_fmac_f32_e32 v105, v102, v102
	v_add_f32_e32 v104, v104, v105
	v_add_f32_e32 v109, v109, v104
	v_lshlrev_b32_e32 v104, 16, v214
	v_and_b32_e32 v105, 0xffff0000, v214
	v_lshlrev_b32_e32 v110, 16, v215
	v_and_b32_e32 v111, 0xffff0000, v215
	v_pk_fma_f32 v[98:99], v[98:99], 0.5, v[110:111] op_sel_hi:[1,0,1]
	v_pk_fma_f32 v[104:105], v[96:97], 0.5, v[104:105] op_sel_hi:[1,0,1]
	v_mul_f32_e32 v97, v99, v99
	v_mul_f32_e32 v96, v105, v105
	v_fmac_f32_e32 v96, v104, v104
	v_fmac_f32_e32 v97, v98, v98
	v_add_f32_e32 v96, v96, v97
	v_add_f32_e32 v96, v109, v96
	v_mov_b32_e32 v97, v96
	s_nop 1
	v_permlane16_swap_b32_e32 v96, v97
	v_cvt_pk_bf16_f32 v110, v100, v101
	v_cvt_pk_bf16_f32 v111, v102, v103
	v_cvt_pk_bf16_f32 v119, v106, v107
	s_waitcnt lgkmcnt(0)
	v_add_f32_e32 v96, v96, v97
	v_mov_b32_e32 v97, v96
	s_nop 1
	v_permlane32_swap_b32_e32 v96, v97
	v_cvt_pk_bf16_f32 v112, v104, v105
	v_cvt_pk_bf16_f32 v113, v98, v99
	v_lshl_add_u64 v[114:115], v[114:115], 0, v[250:251]
	s_nop 1
	v_permlane16_swap_b32_e32 v116, v118
	v_permlane16_swap_b32_e32 v117, v119
	global_store_dwordx4 v[114:115], v[116:119], off
	s_nop 1
	s_nop 1
	v_permlane16_swap_b32_e32 v110, v112
	v_permlane16_swap_b32_e32 v111, v113
	global_store_dwordx4 v[114:115], v[110:113], off offset:256
	s_nop 1
	s_and_saveexec_b64 s[34:35], vcc
	s_cbranch_execz .LBB0_1739
	v_lshlrev_b64 v[98:99], 6, v[208:209]
	v_lshl_add_u64 v[98:99], s[16:17], 0, v[98:99]
	v_lshl_add_u64 v[98:99], s[30:31], 2, v[98:99]
	s_lshl_b32 s12, s47, 2
	v_lshl_add_u64 v[98:99], v[98:99], 0, s[12:13]
	s_waitcnt lgkmcnt(0)
	v_add_f32_e32 v96, v96, v97
	global_store_dword v[98:99], v96, off
.LBB0_1739:
	s_or_b64 exec, exec, s[34:35]
	s_waitcnt vmcnt(16)
	v_permlane16_swap_b32_e32 v204, v206
	v_permlane16_swap_b32_e32 v205, v207
	v_permlane16_swap_b32_e32 v200, v202
	v_permlane16_swap_b32_e32 v201, v203
	v_lshlrev_b64 v[210:211], 11, v[196:197]
	v_lshlrev_b32_e32 v96, 16, v204
	s_waitcnt lgkmcnt(0)
	v_and_b32_e32 v97, 0xffff0000, v204
	v_lshlrev_b32_e32 v98, 16, v205
	v_and_b32_e32 v99, 0xffff0000, v205
	v_pk_fma_f32 v[92:93], v[92:93], 0.5, v[96:97] op_sel_hi:[1,0,1]
	v_pk_fma_f32 v[94:95], v[94:95], 0.5, v[98:99] op_sel_hi:[1,0,1]
	v_cvt_pk_bf16_f32 v100, v92, v93
	v_mul_f32_e32 v93, v93, v93
	v_lshl_add_u64 v[98:99], s[14:15], 0, v[210:211]
	v_fmac_f32_e32 v93, v92, v92
	v_mul_f32_e32 v92, v95, v95
	v_cvt_pk_bf16_f32 v101, v94, v95
	v_lshl_add_u64 v[98:99], v[138:139], 1, v[98:99]
	v_fmac_f32_e32 v92, v94, v94
	v_add_f32_e32 v96, v93, v92
	v_lshlrev_b32_e32 v92, 16, v206
	v_and_b32_e32 v93, 0xffff0000, v206
	v_lshlrev_b32_e32 v94, 16, v207
	v_and_b32_e32 v95, 0xffff0000, v207
	v_pk_fma_f32 v[88:89], v[88:89], 0.5, v[92:93] op_sel_hi:[1,0,1]
	v_pk_fma_f32 v[90:91], v[90:91], 0.5, v[94:95] op_sel_hi:[1,0,1]
	v_cvt_pk_bf16_f32 v102, v88, v89
	v_mul_f32_e32 v89, v89, v89
	v_fmac_f32_e32 v89, v88, v88
	v_mul_f32_e32 v88, v91, v91
	v_fmac_f32_e32 v88, v90, v90
	v_add_f32_e32 v88, v89, v88
	v_add_f32_e32 v93, v96, v88
	v_lshlrev_b32_e32 v88, 16, v200
	v_and_b32_e32 v89, 0xffff0000, v200
	v_lshlrev_b32_e32 v94, 16, v201
	v_and_b32_e32 v95, 0xffff0000, v201
	v_pk_fma_f32 v[86:87], v[86:87], 0.5, v[94:95] op_sel_hi:[1,0,1]
	v_pk_fma_f32 v[84:85], v[84:85], 0.5, v[88:89] op_sel_hi:[1,0,1]
	v_mul_f32_e32 v89, v87, v87
	v_mul_f32_e32 v88, v85, v85
	v_fmac_f32_e32 v88, v84, v84
	v_fmac_f32_e32 v89, v86, v86
	v_add_f32_e32 v88, v88, v89
	v_add_f32_e32 v93, v93, v88
	v_lshlrev_b32_e32 v88, 16, v202
	v_and_b32_e32 v89, 0xffff0000, v202
	v_lshlrev_b32_e32 v94, 16, v203
	v_and_b32_e32 v95, 0xffff0000, v203
	v_pk_fma_f32 v[82:83], v[82:83], 0.5, v[94:95] op_sel_hi:[1,0,1]
	v_pk_fma_f32 v[88:89], v[80:81], 0.5, v[88:89] op_sel_hi:[1,0,1]
	v_mul_f32_e32 v81, v83, v83
	v_mul_f32_e32 v80, v89, v89
	v_fmac_f32_e32 v80, v88, v88
	v_fmac_f32_e32 v81, v82, v82
	v_add_f32_e32 v80, v80, v81
	v_add_f32_e32 v80, v93, v80
	v_mov_b32_e32 v81, v80
	s_nop 1
	v_permlane16_swap_b32_e32 v80, v81
	v_cvt_pk_bf16_f32 v94, v84, v85
	v_cvt_pk_bf16_f32 v95, v86, v87
	v_cvt_pk_bf16_f32 v103, v90, v91
	s_waitcnt lgkmcnt(0)
	v_add_f32_e32 v80, v80, v81
	v_mov_b32_e32 v81, v80
	s_nop 1
	v_permlane32_swap_b32_e32 v80, v81
	v_cvt_pk_bf16_f32 v96, v88, v89
	v_cvt_pk_bf16_f32 v97, v82, v83
	v_lshl_add_u64 v[98:99], v[98:99], 0, v[250:251]
	s_nop 1
	v_permlane16_swap_b32_e32 v100, v102
	v_permlane16_swap_b32_e32 v101, v103
	global_store_dwordx4 v[98:99], v[100:103], off
	s_nop 1
	s_nop 1
	v_permlane16_swap_b32_e32 v94, v96
	v_permlane16_swap_b32_e32 v95, v97
	global_store_dwordx4 v[98:99], v[94:97], off offset:256
	s_nop 1
	s_and_saveexec_b64 s[34:35], vcc
	s_cbranch_execz .LBB0_1741
	v_lshlrev_b64 v[82:83], 6, v[196:197]
	v_lshl_add_u64 v[82:83], s[16:17], 0, v[82:83]
	v_lshl_add_u64 v[82:83], s[30:31], 2, v[82:83]
	s_lshl_b32 s12, s47, 2
	v_lshl_add_u64 v[82:83], v[82:83], 0, s[12:13]
	s_waitcnt lgkmcnt(0)
	v_add_f32_e32 v80, v80, v81
	global_store_dword v[82:83], v80, off
; #define PG8_GAS __attribute__((address_space(1)))
; __device__ __forceinline__ unsigned pk2_(float lo, float hi) { f32x2c_t v = {lo, hi}; bf16x2c_t b = __builtin_convertvector(v, bf16x2c_t); return __builtin_bit_cast(unsigned, b); }
;     __device__ __forceinline__ void operator()(const f32x4 (&acc)[2][2][4][2], const Unit& u, int wr, int wc, int fr, int fq) const {
;     ...
;         for (int ai = 0; ai < 2; ++ai)
; #pragma unroll
;             for (int m = 0; m < 4; ++m) {
;                 const int r = row0 + ai * HALF + m * 16; const size_t off = (size_t)r * 1024 + col0; float ss = 0.f;
; #pragma unroll
;                 for (int bj = 0; bj < 2; ++bj)
; #pragma unroll
;                     for (int n = 0; n < 2; ++n) {
;                         const u32x2v w0 = bsv[ai][m][bj][n]; f32x4 bs;
;                         bs[0] = __builtin_bit_cast(float, w0.x << 16); bs[1] = __builtin_bit_cast(float, w0.x & 0xffff0000u); bs[2] = __builtin_bit_cast(float, w0.y << 16); bs[3] = __builtin_bit_cast(float, w0.y & 0xffff0000u);
;                         const f32x4 v = bs + acc[ai][bj][m][n] * alpha;
;                         { u32x2v w; w.x = pk2_(v[0], v[1]); w.y = pk2_(v[2], v[3]); *(PG8_GAS u32x2v*)(hb + off + bj * HALF + n * 16) = w; }
;                         ss += (v[0] * v[0] + v[1] * v[1]) + (v[2] * v[2] + v[3] * v[3]);
;                     }
;                 ss += __shfl_xor(ss, 16); ss += __shfl_xor(ss, 32);
;                 if (fq == 0) ((PG8_GAS float*)parts)[(size_t)r * 16 + u.pn * 4 + wc] = ss;
;             }
.LBB0_1741:
	s_or_b64 exec, exec, s[34:35]
	s_waitcnt vmcnt(16)
	v_permlane16_swap_b32_e32 v192, v194
	v_permlane16_swap_b32_e32 v193, v195
	v_permlane16_swap_b32_e32 v188, v190
	v_permlane16_swap_b32_e32 v189, v191
	v_lshlrev_b64 v[198:199], 11, v[184:185]
	v_lshlrev_b32_e32 v80, 16, v192
	s_waitcnt lgkmcnt(0)
	v_and_b32_e32 v81, 0xffff0000, v192
	v_lshlrev_b32_e32 v82, 16, v193
	v_and_b32_e32 v83, 0xffff0000, v193
	v_pk_fma_f32 v[76:77], v[76:77], 0.5, v[80:81] op_sel_hi:[1,0,1]
	v_pk_fma_f32 v[78:79], v[78:79], 0.5, v[82:83] op_sel_hi:[1,0,1]
	v_cvt_pk_bf16_f32 v84, v76, v77
	v_mul_f32_e32 v77, v77, v77
	v_lshl_add_u64 v[82:83], s[14:15], 0, v[198:199]
	v_fmac_f32_e32 v77, v76, v76
	v_mul_f32_e32 v76, v79, v79
	v_cvt_pk_bf16_f32 v85, v78, v79
	v_lshl_add_u64 v[82:83], v[138:139], 1, v[82:83]
	v_fmac_f32_e32 v76, v78, v78
	v_add_f32_e32 v80, v77, v76
	v_lshlrev_b32_e32 v76, 16, v194
	v_and_b32_e32 v77, 0xffff0000, v194
	v_lshlrev_b32_e32 v78, 16, v195
	v_and_b32_e32 v79, 0xffff0000, v195
	v_pk_fma_f32 v[72:73], v[72:73], 0.5, v[76:77] op_sel_hi:[1,0,1]
	v_pk_fma_f32 v[74:75], v[74:75], 0.5, v[78:79] op_sel_hi:[1,0,1]
	v_cvt_pk_bf16_f32 v86, v72, v73
	v_mul_f32_e32 v73, v73, v73
	v_fmac_f32_e32 v73, v72, v72
	v_mul_f32_e32 v72, v75, v75
	v_fmac_f32_e32 v72, v74, v74
	v_add_f32_e32 v72, v73, v72
	v_add_f32_e32 v77, v80, v72
	v_lshlrev_b32_e32 v72, 16, v188
	v_and_b32_e32 v73, 0xffff0000, v188
	v_lshlrev_b32_e32 v78, 16, v189
	v_and_b32_e32 v79, 0xffff0000, v189
	v_pk_fma_f32 v[70:71], v[70:71], 0.5, v[78:79] op_sel_hi:[1,0,1]
	v_pk_fma_f32 v[68:69], v[68:69], 0.5, v[72:73] op_sel_hi:[1,0,1]
	v_mul_f32_e32 v73, v71, v71
	v_mul_f32_e32 v72, v69, v69
	v_fmac_f32_e32 v72, v68, v68
	v_fmac_f32_e32 v73, v70, v70
	v_add_f32_e32 v72, v72, v73
	v_add_f32_e32 v77, v77, v72
	v_lshlrev_b32_e32 v72, 16, v190
	v_and_b32_e32 v73, 0xffff0000, v190
	v_lshlrev_b32_e32 v78, 16, v191
	v_and_b32_e32 v79, 0xffff0000, v191
	v_pk_fma_f32 v[66:67], v[66:67], 0.5, v[78:79] op_sel_hi:[1,0,1]
	v_pk_fma_f32 v[72:73], v[64:65], 0.5, v[72:73] op_sel_hi:[1,0,1]
	v_mul_f32_e32 v65, v67, v67
	v_mul_f32_e32 v64, v73, v73
	v_fmac_f32_e32 v64, v72, v72
	v_fmac_f32_e32 v65, v66, v66
	v_add_f32_e32 v64, v64, v65
	v_add_f32_e32 v64, v77, v64
	v_mov_b32_e32 v65, v64
	s_nop 1
	v_permlane16_swap_b32_e32 v64, v65
	v_cvt_pk_bf16_f32 v78, v68, v69
	v_cvt_pk_bf16_f32 v79, v70, v71
	v_cvt_pk_bf16_f32 v87, v74, v75
	s_waitcnt lgkmcnt(0)
	v_add_f32_e32 v64, v64, v65
	v_mov_b32_e32 v65, v64
	s_nop 1
	v_permlane32_swap_b32_e32 v64, v65
	v_cvt_pk_bf16_f32 v80, v72, v73
	v_cvt_pk_bf16_f32 v81, v66, v67
	v_lshl_add_u64 v[82:83], v[82:83], 0, v[250:251]
	s_nop 1
	v_permlane16_swap_b32_e32 v84, v86
	v_permlane16_swap_b32_e32 v85, v87
	global_store_dwordx4 v[82:83], v[84:87], off
	s_nop 1
	s_nop 1
	v_permlane16_swap_b32_e32 v78, v80
	v_permlane16_swap_b32_e32 v79, v81
	global_store_dwordx4 v[82:83], v[78:81], off offset:256
	s_nop 1
	s_and_saveexec_b64 s[34:35], vcc
	s_cbranch_execz .LBB0_1743
	v_lshlrev_b64 v[66:67], 6, v[184:185]
	v_lshl_add_u64 v[66:67], s[16:17], 0, v[66:67]
	v_lshl_add_u64 v[66:67], s[30:31], 2, v[66:67]
	s_lshl_b32 s12, s47, 2
	v_lshl_add_u64 v[66:67], v[66:67], 0, s[12:13]
	s_waitcnt lgkmcnt(0)
	v_add_f32_e32 v64, v64, v65
	global_store_dword v[66:67], v64, off
.LBB0_1743:
	s_or_b64 exec, exec, s[34:35]
	s_waitcnt vmcnt(16)
	v_permlane16_swap_b32_e32 v180, v182
	v_permlane16_swap_b32_e32 v181, v183
	v_permlane16_swap_b32_e32 v176, v178
	v_permlane16_swap_b32_e32 v177, v179
	v_lshlrev_b64 v[186:187], 11, v[172:173]
	v_lshlrev_b32_e32 v64, 16, v180
	s_waitcnt lgkmcnt(0)
	v_and_b32_e32 v65, 0xffff0000, v180
	v_lshlrev_b32_e32 v66, 16, v181
	v_and_b32_e32 v67, 0xffff0000, v181
	v_pk_fma_f32 v[60:61], v[60:61], 0.5, v[64:65] op_sel_hi:[1,0,1]
	v_pk_fma_f32 v[62:63], v[62:63], 0.5, v[66:67] op_sel_hi:[1,0,1]
	v_cvt_pk_bf16_f32 v68, v60, v61
	v_mul_f32_e32 v61, v61, v61
	v_lshl_add_u64 v[66:67], s[14:15], 0, v[186:187]
	v_fmac_f32_e32 v61, v60, v60
	v_mul_f32_e32 v60, v63, v63
	v_cvt_pk_bf16_f32 v69, v62, v63
	v_lshl_add_u64 v[66:67], v[138:139], 1, v[66:67]
	v_fmac_f32_e32 v60, v62, v62
	v_add_f32_e32 v64, v61, v60
	v_lshlrev_b32_e32 v60, 16, v182
	v_and_b32_e32 v61, 0xffff0000, v182
	v_lshlrev_b32_e32 v62, 16, v183
	v_and_b32_e32 v63, 0xffff0000, v183
	v_pk_fma_f32 v[56:57], v[56:57], 0.5, v[60:61] op_sel_hi:[1,0,1]
	v_pk_fma_f32 v[58:59], v[58:59], 0.5, v[62:63] op_sel_hi:[1,0,1]
	v_cvt_pk_bf16_f32 v70, v56, v57
	v_mul_f32_e32 v57, v57, v57
	v_fmac_f32_e32 v57, v56, v56
	v_mul_f32_e32 v56, v59, v59
	v_fmac_f32_e32 v56, v58, v58
	v_add_f32_e32 v56, v57, v56
	v_add_f32_e32 v61, v64, v56
	v_lshlrev_b32_e32 v56, 16, v176
	v_and_b32_e32 v57, 0xffff0000, v176
	v_lshlrev_b32_e32 v62, 16, v177
	v_and_b32_e32 v63, 0xffff0000, v177
	v_pk_fma_f32 v[54:55], v[54:55], 0.5, v[62:63] op_sel_hi:[1,0,1]
	v_pk_fma_f32 v[52:53], v[52:53], 0.5, v[56:57] op_sel_hi:[1,0,1]
	v_mul_f32_e32 v57, v55, v55
	v_mul_f32_e32 v56, v53, v53
	v_fmac_f32_e32 v56, v52, v52
	v_fmac_f32_e32 v57, v54, v54
	v_add_f32_e32 v56, v56, v57
	v_add_f32_e32 v61, v61, v56
	v_lshlrev_b32_e32 v56, 16, v178
	v_and_b32_e32 v57, 0xffff0000, v178
	v_lshlrev_b32_e32 v62, 16, v179
	v_and_b32_e32 v63, 0xffff0000, v179
	v_pk_fma_f32 v[50:51], v[50:51], 0.5, v[62:63] op_sel_hi:[1,0,1]
	v_pk_fma_f32 v[56:57], v[48:49], 0.5, v[56:57] op_sel_hi:[1,0,1]
	v_mul_f32_e32 v49, v51, v51
	v_mul_f32_e32 v48, v57, v57
	v_fmac_f32_e32 v48, v56, v56
	v_fmac_f32_e32 v49, v50, v50
	v_add_f32_e32 v48, v48, v49
	v_add_f32_e32 v48, v61, v48
	v_mov_b32_e32 v49, v48
	s_nop 1
	v_permlane16_swap_b32_e32 v48, v49
	v_cvt_pk_bf16_f32 v62, v52, v53
	v_cvt_pk_bf16_f32 v63, v54, v55
	v_cvt_pk_bf16_f32 v71, v58, v59
	s_waitcnt lgkmcnt(0)
	v_add_f32_e32 v48, v48, v49
	v_mov_b32_e32 v49, v48
	s_nop 1
	v_permlane32_swap_b32_e32 v48, v49
	v_cvt_pk_bf16_f32 v64, v56, v57
	v_cvt_pk_bf16_f32 v65, v50, v51
	v_lshl_add_u64 v[66:67], v[66:67], 0, v[250:251]
	s_nop 1
	v_permlane16_swap_b32_e32 v68, v70
	v_permlane16_swap_b32_e32 v69, v71
	global_store_dwordx4 v[66:67], v[68:71], off
	s_nop 1
	s_nop 1
	v_permlane16_swap_b32_e32 v62, v64
	v_permlane16_swap_b32_e32 v63, v65
	global_store_dwordx4 v[66:67], v[62:65], off offset:256
	s_nop 1
	s_and_saveexec_b64 s[34:35], vcc
	s_cbranch_execz .LBB0_1745
	v_lshlrev_b64 v[50:51], 6, v[172:173]
	v_lshl_add_u64 v[50:51], s[16:17], 0, v[50:51]
	v_lshl_add_u64 v[50:51], s[30:31], 2, v[50:51]
	s_lshl_b32 s12, s47, 2
	v_lshl_add_u64 v[50:51], v[50:51], 0, s[12:13]
	s_waitcnt lgkmcnt(0)
	v_add_f32_e32 v48, v48, v49
	global_store_dword v[50:51], v48, off
; #define PG8_GAS __attribute__((address_space(1)))
; __device__ __forceinline__ unsigned pk2_(float lo, float hi) { f32x2c_t v = {lo, hi}; bf16x2c_t b = __builtin_convertvector(v, bf16x2c_t); return __builtin_bit_cast(unsigned, b); }
;     __device__ __forceinline__ void operator()(const f32x4 (&acc)[2][2][4][2], const Unit& u, int wr, int wc, int fr, int fq) const {
;     ...
;         for (int ai = 0; ai < 2; ++ai)
; #pragma unroll
;             for (int m = 0; m < 4; ++m) {
;                 const int r = row0 + ai * HALF + m * 16; const size_t off = (size_t)r * 1024 + col0; float ss = 0.f;
; #pragma unroll
;                 for (int bj = 0; bj < 2; ++bj)
; #pragma unroll
;                     for (int n = 0; n < 2; ++n) {
;                         const u32x2v w0 = bsv[ai][m][bj][n]; f32x4 bs;
;                         bs[0] = __builtin_bit_cast(float, w0.x << 16); bs[1] = __builtin_bit_cast(float, w0.x & 0xffff0000u); bs[2] = __builtin_bit_cast(float, w0.y << 16); bs[3] = __builtin_bit_cast(float, w0.y & 0xffff0000u);
;                         const f32x4 v = bs + acc[ai][bj][m][n] * alpha;
;                         { u32x2v w; w.x = pk2_(v[0], v[1]); w.y = pk2_(v[2], v[3]); *(PG8_GAS u32x2v*)(hb + off + bj * HALF + n * 16) = w; }
;                         ss += (v[0] * v[0] + v[1] * v[1]) + (v[2] * v[2] + v[3] * v[3]);
;                     }
;                 ss += __shfl_xor(ss, 16); ss += __shfl_xor(ss, 32);
;                 if (fq == 0) ((PG8_GAS float*)parts)[(size_t)r * 16 + u.pn * 4 + wc] = ss;
;             }
.LBB0_1745:
	s_or_b64 exec, exec, s[34:35]
	s_waitcnt vmcnt(16)
	v_permlane16_swap_b32_e32 v168, v170
	v_permlane16_swap_b32_e32 v169, v171
	v_permlane16_swap_b32_e32 v164, v166
	v_permlane16_swap_b32_e32 v165, v167
	v_lshlrev_b64 v[174:175], 11, v[160:161]
	v_lshlrev_b32_e32 v48, 16, v168
	s_waitcnt lgkmcnt(0)
	v_and_b32_e32 v49, 0xffff0000, v168
	v_lshlrev_b32_e32 v50, 16, v169
	v_and_b32_e32 v51, 0xffff0000, v169
	v_pk_fma_f32 v[44:45], v[44:45], 0.5, v[48:49] op_sel_hi:[1,0,1]
	v_pk_fma_f32 v[46:47], v[46:47], 0.5, v[50:51] op_sel_hi:[1,0,1]
	v_cvt_pk_bf16_f32 v52, v44, v45
	v_mul_f32_e32 v45, v45, v45
	v_lshl_add_u64 v[50:51], s[14:15], 0, v[174:175]
	v_fmac_f32_e32 v45, v44, v44
	v_mul_f32_e32 v44, v47, v47
	v_cvt_pk_bf16_f32 v53, v46, v47
	v_lshl_add_u64 v[50:51], v[138:139], 1, v[50:51]
	v_fmac_f32_e32 v44, v46, v46
	v_add_f32_e32 v48, v45, v44
	v_lshlrev_b32_e32 v44, 16, v170
	v_and_b32_e32 v45, 0xffff0000, v170
	v_lshlrev_b32_e32 v46, 16, v171
	v_and_b32_e32 v47, 0xffff0000, v171
	v_pk_fma_f32 v[40:41], v[40:41], 0.5, v[44:45] op_sel_hi:[1,0,1]
	v_pk_fma_f32 v[42:43], v[42:43], 0.5, v[46:47] op_sel_hi:[1,0,1]
	v_cvt_pk_bf16_f32 v54, v40, v41
	v_mul_f32_e32 v41, v41, v41
	v_fmac_f32_e32 v41, v40, v40
	v_mul_f32_e32 v40, v43, v43
	v_fmac_f32_e32 v40, v42, v42
	v_add_f32_e32 v40, v41, v40
	v_add_f32_e32 v45, v48, v40
	v_lshlrev_b32_e32 v40, 16, v164
	v_and_b32_e32 v41, 0xffff0000, v164
	v_lshlrev_b32_e32 v46, 16, v165
	v_and_b32_e32 v47, 0xffff0000, v165
	v_pk_fma_f32 v[38:39], v[38:39], 0.5, v[46:47] op_sel_hi:[1,0,1]
	v_pk_fma_f32 v[36:37], v[36:37], 0.5, v[40:41] op_sel_hi:[1,0,1]
	v_mul_f32_e32 v41, v39, v39
	v_mul_f32_e32 v40, v37, v37
	v_fmac_f32_e32 v40, v36, v36
	v_fmac_f32_e32 v41, v38, v38
	v_add_f32_e32 v40, v40, v41
	v_add_f32_e32 v45, v45, v40
	v_lshlrev_b32_e32 v40, 16, v166
	v_and_b32_e32 v41, 0xffff0000, v166
	v_lshlrev_b32_e32 v46, 16, v167
	v_and_b32_e32 v47, 0xffff0000, v167
	v_pk_fma_f32 v[34:35], v[34:35], 0.5, v[46:47] op_sel_hi:[1,0,1]
	v_pk_fma_f32 v[40:41], v[32:33], 0.5, v[40:41] op_sel_hi:[1,0,1]
	v_mul_f32_e32 v33, v35, v35
	v_mul_f32_e32 v32, v41, v41
	v_fmac_f32_e32 v32, v40, v40
	v_fmac_f32_e32 v33, v34, v34
	v_add_f32_e32 v32, v32, v33
	v_add_f32_e32 v32, v45, v32
	v_mov_b32_e32 v33, v32
	s_nop 1
	v_permlane16_swap_b32_e32 v32, v33
	v_cvt_pk_bf16_f32 v46, v36, v37
	v_cvt_pk_bf16_f32 v47, v38, v39
	v_cvt_pk_bf16_f32 v55, v42, v43
	s_waitcnt lgkmcnt(0)
	v_add_f32_e32 v32, v32, v33
	v_mov_b32_e32 v33, v32
	s_nop 1
	v_permlane32_swap_b32_e32 v32, v33
	v_cvt_pk_bf16_f32 v48, v40, v41
	v_cvt_pk_bf16_f32 v49, v34, v35
	v_lshl_add_u64 v[50:51], v[50:51], 0, v[250:251]
	s_nop 1
	v_permlane16_swap_b32_e32 v52, v54
	v_permlane16_swap_b32_e32 v53, v55
	global_store_dwordx4 v[50:51], v[52:55], off
	s_nop 1
	s_nop 1
	v_permlane16_swap_b32_e32 v46, v48
	v_permlane16_swap_b32_e32 v47, v49
	global_store_dwordx4 v[50:51], v[46:49], off offset:256
	s_nop 1
	s_and_saveexec_b64 s[34:35], vcc
	s_cbranch_execz .LBB0_1747
	v_lshlrev_b64 v[34:35], 6, v[160:161]
	v_lshl_add_u64 v[34:35], s[16:17], 0, v[34:35]
	v_lshl_add_u64 v[34:35], s[30:31], 2, v[34:35]
	s_lshl_b32 s12, s47, 2
	v_lshl_add_u64 v[34:35], v[34:35], 0, s[12:13]
	s_waitcnt lgkmcnt(0)
	v_add_f32_e32 v32, v32, v33
	global_store_dword v[34:35], v32, off
; #define PG8_GAS __attribute__((address_space(1)))
; __device__ __forceinline__ unsigned pk2_(float lo, float hi) { f32x2c_t v = {lo, hi}; bf16x2c_t b = __builtin_convertvector(v, bf16x2c_t); return __builtin_bit_cast(unsigned, b); }
;     __device__ __forceinline__ void operator()(const f32x4 (&acc)[2][2][4][2], const Unit& u, int wr, int wc, int fr, int fq) const {
;     ...
;         for (int ai = 0; ai < 2; ++ai)
; #pragma unroll
;             for (int m = 0; m < 4; ++m) {
;                 const int r = row0 + ai * HALF + m * 16; const size_t off = (size_t)r * 1024 + col0; float ss = 0.f;
; #pragma unroll
;                 for (int bj = 0; bj < 2; ++bj)
; #pragma unroll
;                     for (int n = 0; n < 2; ++n) {
;                         const u32x2v w0 = bsv[ai][m][bj][n]; f32x4 bs;
;                         bs[0] = __builtin_bit_cast(float, w0.x << 16); bs[1] = __builtin_bit_cast(float, w0.x & 0xffff0000u); bs[2] = __builtin_bit_cast(float, w0.y << 16); bs[3] = __builtin_bit_cast(float, w0.y & 0xffff0000u);
;                         const f32x4 v = bs + acc[ai][bj][m][n] * alpha;
;                         { u32x2v w; w.x = pk2_(v[0], v[1]); w.y = pk2_(v[2], v[3]); *(PG8_GAS u32x2v*)(hb + off + bj * HALF + n * 16) = w; }
;                         ss += (v[0] * v[0] + v[1] * v[1]) + (v[2] * v[2] + v[3] * v[3]);
;                     }
;                 ss += __shfl_xor(ss, 16); ss += __shfl_xor(ss, 32);
;                 if (fq == 0) ((PG8_GAS float*)parts)[(size_t)r * 16 + u.pn * 4 + wc] = ss;
;             }
.LBB0_1747:
	s_or_b64 exec, exec, s[34:35]
	s_waitcnt vmcnt(16)
	v_permlane16_swap_b32_e32 v156, v158
	v_permlane16_swap_b32_e32 v157, v159
	v_permlane16_swap_b32_e32 v152, v154
	v_permlane16_swap_b32_e32 v153, v155
	v_lshlrev_b64 v[162:163], 11, v[148:149]
	v_lshlrev_b32_e32 v32, 16, v156
	s_waitcnt lgkmcnt(0)
	v_and_b32_e32 v33, 0xffff0000, v156
	v_lshlrev_b32_e32 v34, 16, v157
	v_and_b32_e32 v35, 0xffff0000, v157
	v_pk_fma_f32 v[28:29], v[28:29], 0.5, v[32:33] op_sel_hi:[1,0,1]
	v_pk_fma_f32 v[30:31], v[30:31], 0.5, v[34:35] op_sel_hi:[1,0,1]
	v_cvt_pk_bf16_f32 v36, v28, v29
	v_mul_f32_e32 v29, v29, v29
	v_lshl_add_u64 v[34:35], s[14:15], 0, v[162:163]
	v_fmac_f32_e32 v29, v28, v28
	v_mul_f32_e32 v28, v31, v31
	v_cvt_pk_bf16_f32 v37, v30, v31
	v_lshl_add_u64 v[34:35], v[138:139], 1, v[34:35]
	v_fmac_f32_e32 v28, v30, v30
	v_add_f32_e32 v32, v29, v28
	v_lshlrev_b32_e32 v28, 16, v158
	v_and_b32_e32 v29, 0xffff0000, v158
	v_lshlrev_b32_e32 v30, 16, v159
	v_and_b32_e32 v31, 0xffff0000, v159
	v_pk_fma_f32 v[24:25], v[24:25], 0.5, v[28:29] op_sel_hi:[1,0,1]
	v_pk_fma_f32 v[26:27], v[26:27], 0.5, v[30:31] op_sel_hi:[1,0,1]
	v_cvt_pk_bf16_f32 v38, v24, v25
	v_mul_f32_e32 v25, v25, v25
	v_fmac_f32_e32 v25, v24, v24
	v_mul_f32_e32 v24, v27, v27
	v_fmac_f32_e32 v24, v26, v26
	v_add_f32_e32 v24, v25, v24
	v_add_f32_e32 v29, v32, v24
	v_lshlrev_b32_e32 v24, 16, v152
	v_and_b32_e32 v25, 0xffff0000, v152
	v_lshlrev_b32_e32 v30, 16, v153
	v_and_b32_e32 v31, 0xffff0000, v153
	v_pk_fma_f32 v[22:23], v[22:23], 0.5, v[30:31] op_sel_hi:[1,0,1]
	v_pk_fma_f32 v[20:21], v[20:21], 0.5, v[24:25] op_sel_hi:[1,0,1]
	v_mul_f32_e32 v25, v23, v23
	v_mul_f32_e32 v24, v21, v21
	v_fmac_f32_e32 v24, v20, v20
	v_fmac_f32_e32 v25, v22, v22
	v_add_f32_e32 v24, v24, v25
	v_add_f32_e32 v29, v29, v24
	v_lshlrev_b32_e32 v24, 16, v154
	v_and_b32_e32 v25, 0xffff0000, v154
	v_lshlrev_b32_e32 v30, 16, v155
	v_and_b32_e32 v31, 0xffff0000, v155
	v_pk_fma_f32 v[18:19], v[18:19], 0.5, v[30:31] op_sel_hi:[1,0,1]
	v_pk_fma_f32 v[24:25], v[16:17], 0.5, v[24:25] op_sel_hi:[1,0,1]
	v_mul_f32_e32 v17, v19, v19
	v_mul_f32_e32 v16, v25, v25
	v_fmac_f32_e32 v16, v24, v24
	v_fmac_f32_e32 v17, v18, v18
	v_add_f32_e32 v16, v16, v17
	v_add_f32_e32 v16, v29, v16
	v_mov_b32_e32 v17, v16
	s_nop 1
	v_permlane16_swap_b32_e32 v16, v17
	v_cvt_pk_bf16_f32 v30, v20, v21
	v_cvt_pk_bf16_f32 v31, v22, v23
	v_cvt_pk_bf16_f32 v39, v26, v27
	s_waitcnt lgkmcnt(0)
	v_add_f32_e32 v16, v16, v17
	v_mov_b32_e32 v17, v16
	s_nop 1
	v_permlane32_swap_b32_e32 v16, v17
	v_cvt_pk_bf16_f32 v32, v24, v25
	v_cvt_pk_bf16_f32 v33, v18, v19
	v_lshl_add_u64 v[34:35], v[34:35], 0, v[250:251]
	s_nop 1
	v_permlane16_swap_b32_e32 v36, v38
	v_permlane16_swap_b32_e32 v37, v39
	global_store_dwordx4 v[34:35], v[36:39], off
	s_nop 1
	s_nop 1
	v_permlane16_swap_b32_e32 v30, v32
	v_permlane16_swap_b32_e32 v31, v33
	global_store_dwordx4 v[34:35], v[30:33], off offset:256
	s_nop 1
	s_and_saveexec_b64 s[34:35], vcc
	s_cbranch_execz .LBB0_1749
	v_lshlrev_b64 v[18:19], 6, v[148:149]
	v_lshl_add_u64 v[18:19], s[16:17], 0, v[18:19]
	v_lshl_add_u64 v[18:19], s[30:31], 2, v[18:19]
	s_lshl_b32 s12, s47, 2
	v_lshl_add_u64 v[18:19], v[18:19], 0, s[12:13]
	s_waitcnt lgkmcnt(0)
	v_add_f32_e32 v16, v16, v17
	global_store_dword v[18:19], v16, off
.LBB0_1749:
	s_or_b64 exec, exec, s[34:35]
	s_waitcnt vmcnt(16)
	v_permlane16_swap_b32_e32 v144, v146
	v_permlane16_swap_b32_e32 v145, v147
	v_permlane16_swap_b32_e32 v140, v142
	v_permlane16_swap_b32_e32 v141, v143
	v_lshlrev_b64 v[150:151], 11, v[136:137]
	v_lshlrev_b32_e32 v16, 16, v144
	s_waitcnt lgkmcnt(0)
	v_and_b32_e32 v17, 0xffff0000, v144
	v_lshlrev_b32_e32 v18, 16, v145
	v_and_b32_e32 v19, 0xffff0000, v145
	v_pk_fma_f32 v[12:13], v[12:13], 0.5, v[16:17] op_sel_hi:[1,0,1]
	v_pk_fma_f32 v[14:15], v[14:15], 0.5, v[18:19] op_sel_hi:[1,0,1]
	v_cvt_pk_bf16_f32 v20, v12, v13
	v_mul_f32_e32 v13, v13, v13
	v_lshl_add_u64 v[18:19], s[14:15], 0, v[150:151]
	v_fmac_f32_e32 v13, v12, v12
	v_mul_f32_e32 v12, v15, v15
	v_cvt_pk_bf16_f32 v21, v14, v15
	v_lshl_add_u64 v[18:19], v[138:139], 1, v[18:19]
	v_fmac_f32_e32 v12, v14, v14
	v_add_f32_e32 v16, v13, v12
	v_lshlrev_b32_e32 v12, 16, v146
	v_and_b32_e32 v13, 0xffff0000, v146
	v_lshlrev_b32_e32 v14, 16, v147
	v_and_b32_e32 v15, 0xffff0000, v147
	v_pk_fma_f32 v[8:9], v[8:9], 0.5, v[12:13] op_sel_hi:[1,0,1]
	v_pk_fma_f32 v[10:11], v[10:11], 0.5, v[14:15] op_sel_hi:[1,0,1]
	v_cvt_pk_bf16_f32 v22, v8, v9
	v_mul_f32_e32 v9, v9, v9
	v_fmac_f32_e32 v9, v8, v8
	v_mul_f32_e32 v8, v11, v11
	v_fmac_f32_e32 v8, v10, v10
	v_add_f32_e32 v8, v9, v8
	v_add_f32_e32 v13, v16, v8
	v_lshlrev_b32_e32 v8, 16, v140
	v_and_b32_e32 v9, 0xffff0000, v140
	v_lshlrev_b32_e32 v14, 16, v141
	v_and_b32_e32 v15, 0xffff0000, v141
	v_pk_fma_f32 v[6:7], v[6:7], 0.5, v[14:15] op_sel_hi:[1,0,1]
	v_pk_fma_f32 v[4:5], v[4:5], 0.5, v[8:9] op_sel_hi:[1,0,1]
	v_mul_f32_e32 v9, v7, v7
	v_mul_f32_e32 v8, v5, v5
	v_fmac_f32_e32 v8, v4, v4
	v_fmac_f32_e32 v9, v6, v6
	v_add_f32_e32 v8, v8, v9
	v_add_f32_e32 v13, v13, v8
	v_lshlrev_b32_e32 v8, 16, v142
	v_and_b32_e32 v9, 0xffff0000, v142
	v_lshlrev_b32_e32 v14, 16, v143
	v_and_b32_e32 v15, 0xffff0000, v143
	v_pk_fma_f32 v[2:3], v[2:3], 0.5, v[14:15] op_sel_hi:[1,0,1]
	v_pk_fma_f32 v[8:9], v[0:1], 0.5, v[8:9] op_sel_hi:[1,0,1]
	v_mul_f32_e32 v1, v3, v3
	v_mul_f32_e32 v0, v9, v9
	v_fmac_f32_e32 v0, v8, v8
	v_fmac_f32_e32 v1, v2, v2
	v_add_f32_e32 v0, v0, v1
	v_add_f32_e32 v0, v13, v0
	v_mov_b32_e32 v1, v0
	s_nop 1
	v_permlane16_swap_b32_e32 v0, v1
	v_cvt_pk_bf16_f32 v14, v4, v5
	v_cvt_pk_bf16_f32 v15, v6, v7
	v_cvt_pk_bf16_f32 v23, v10, v11
	s_waitcnt lgkmcnt(0)
	v_add_f32_e32 v0, v0, v1
	v_mov_b32_e32 v1, v0
	s_nop 1
	v_permlane32_swap_b32_e32 v0, v1
	v_cvt_pk_bf16_f32 v16, v8, v9
	v_cvt_pk_bf16_f32 v17, v2, v3
	v_lshl_add_u64 v[18:19], v[18:19], 0, v[250:251]
	s_nop 1
	v_permlane16_swap_b32_e32 v20, v22
	v_permlane16_swap_b32_e32 v21, v23
	global_store_dwordx4 v[18:19], v[20:23], off
	s_nop 1
	s_nop 1
	v_permlane16_swap_b32_e32 v14, v16
	v_permlane16_swap_b32_e32 v15, v17
	global_store_dwordx4 v[18:19], v[14:17], off offset:256
	s_nop 1
	s_and_saveexec_b64 s[34:35], vcc
	s_cbranch_execz .LBB0_1751
	v_lshlrev_b64 v[2:3], 6, v[136:137]
	v_lshl_add_u64 v[2:3], s[16:17], 0, v[2:3]
	v_lshl_add_u64 v[2:3], s[30:31], 2, v[2:3]
	s_lshl_b32 s12, s47, 2
	v_lshl_add_u64 v[2:3], v[2:3], 0, s[12:13]
	s_waitcnt lgkmcnt(0)
	v_add_f32_e32 v0, v0, v1
	global_store_dword v[2:3], v0, off
